# gemm1/2/3 K-loops rewritten by hand: BK=64, full 128-B line LDS-DMA pieces (8 rows x 128 B), XOR-swizzled LDS image, 2x32 KB double buffer (LDS 66560 B); bf16 MFMA f32 accumulate unchanged
# speedup vs baseline: 1.0761x; 1.0578x over previous
; __device__ __forceinline__ int tid_() { int t = threadIdx.x; asm volatile("" : "+v"(t)); return t; }
; __device__ __forceinline__ GemmOps gemm_ops(const u16* A, int lda, const u16* B, int ldb) {
;   const int lane = tid_() & 63, wid = tid_() >> 6, rr = lane >> 2, c = lane & 3;
;   const int R0 = wid * 16 + rr, R1 = (wid + 4) * 16 + rr;
;   GemmOps g;
;   g.a0 = A + (size_t)R0 * lda + ((c ^ ((R0 >> 2) & 3)) << 3);
;   g.a1 = A + (size_t)R1 * lda + ((c ^ ((R1 >> 2) & 3)) << 3);
;   g.b0 = B + (size_t)R0 * ldb + ((c ^ ((R0 >> 2) & 3)) << 3);
;   g.b1 = B + (size_t)R1 * ldb + ((c ^ ((R1 >> 2) & 3)) << 3);
;   return g;
; }
; __device__ __forceinline__ void gemm_issue(const GemmOps& g, int kt, int buf, char* L) {
;   const int wid = tid_() >> 6;
;   char* sb = L + buf * GEMM_STAGE_B;
;   __builtin_amdgcn_global_load_lds((const unsigned*)(g.a0 + kt * 32), (unsigned*)(sb + wid * 1024), 16, 0, 0);
;   __builtin_amdgcn_global_load_lds((const unsigned*)(g.a1 + kt * 32), (unsigned*)(sb + (wid + 4) * 1024), 16, 0, 0);
;   __builtin_amdgcn_global_load_lds((const unsigned*)(g.b0 + kt * 32), (unsigned*)(sb + 8192 + wid * 1024), 16, 0, 0);
;   __builtin_amdgcn_global_load_lds((const unsigned*)(g.b1 + kt * 32), (unsigned*)(sb + 8192 + (wid + 4) * 1024), 16, 0, 0);
; }
; __device__ __forceinline__ void gemm_prologue(const GemmOps& g, u16* lds) {
;   gemm_issue(g, 0, 0, (char*)lds); gemm_issue(g, 1, 1, (char*)lds);
; }
; __device__ void ph_gemm1(const P& p, u16* lds) {
;   const int wid = tid_() >> 6, wm = wid >> 1, wn = wid & 1;
;   const int NT = 23, NTILES = 264 * NT;
;   int it = blockIdx.x;
;   if (it >= NTILES) return;
;   auto ops = [&](int t) __attribute__((always_inline)) { return gemm_ops(p_Abf + (size_t)(t / NT) * 128 * DM, DM, p_WinT + (size_t)(t % NT) * 128 * DM, DM); };
;   GemmOps g = ops(it);
;   __syncthreads();
;   gemm_prologue(g, lds);
.LBB0_70:
	s_cmp_lt_i32 s6, 2
	s_cselect_b64 s[0:1], -1, 0
	s_cmp_gt_i32 s7, 1
	s_cselect_b64 s[2:3], -1, 0
	s_and_b64 s[0:1], s[0:1], s[2:3]
	s_andn2_b64 vcc, exec, s[0:1]
	s_cbranch_vccnz .LBB0_140
	v_readlane_b32 s0, v228, 0
	v_mov_b32_e32 v0, v220
	s_cmpk_gt_i32 s0, 0x17b7
	v_readlane_b32 s1, v228, 1
	s_cbranch_scc1 .LBB0_86
	v_readlane_b32 s0, v228, 2
	v_readlane_b32 s6, v228, 8
	v_readlane_b32 s8, v228, 0
	s_and_b32 s81, s8, 7
	s_lshr_b32 s82, s8, 3
	s_mul_hi_u32 s83, s82, 0x1642c86
	s_mul_i32 s84, s83, 184
	s_sub_u32 s84, s82, s84
	s_cmp_lt_u32 s83, 4
	s_cselect_b32 s85, 3, 0
	s_cselect_b32 s86, 7, 0
	s_lshr_b32 s87, s84, s85
	s_and_b32 s84, s84, s86
	s_lshl_b32 s83, s83, 3
	s_add_u32 s83, s83, s84
	s_mul_i32 s81, s81, 33
	s_add_u32 s81, s81, s83
	s_mul_i32 s81, s81, 23
	s_add_u32 s80, s81, s87
	v_readlane_b32 s7, v228, 9
	s_add_u32 s12, s6, 0x3f40000
	s_mul_hi_i32 s0, s80, 0xb21642c9
	v_readlane_b32 s1, v228, 3
	s_addc_u32 s13, s7, 0
	s_add_i32 s0, s0, s80
	s_lshr_b32 s1, s0, 31
	s_ashr_i32 s0, s0, 4
	s_add_i32 s0, s0, s1
	v_readlane_b32 s2, v228, 4
	v_readlane_b32 s3, v228, 5
	s_ashr_i32 s1, s0, 31
	s_lshl_b64 s[2:3], s[0:1], 18
	s_add_u32 s2, s12, s2
	s_mul_i32 s0, s0, 23
	v_mov_b32_e32 v1, v220
	v_mov_b32_e32 v2, v220
	s_addc_u32 s3, s13, s3
	s_sub_i32 s0, s80, s0
	s_ashr_i32 s1, s0, 31
	v_lshrrev_b32_e32 v5, 4, v1
	v_lshrrev_b32_e32 v3, 2, v1
	v_ashrrev_i32_e32 v2, 2, v2
	v_xor_b32_e32 v1, v5, v1
	s_lshl_b64 s[0:1], s[0:1], 18
	v_bfi_b32 v2, -16, v2, v3
	v_lshlrev_b32_e32 v1, 4, v1
	s_add_u32 s0, s6, s0
	v_add_u32_e32 v4, 64, v2
	v_ashrrev_i32_e32 v3, 31, v2
	v_and_b32_e32 v64, 48, v1
	v_mov_b32_e32 v1, v220
	s_addc_u32 s1, s7, s1
	s_mov_b64 s[88:89], s[2:3]
	s_mov_b64 s[90:91], s[0:1]
	v_lshlrev_b64 v[2:3], 11, v[2:3]
	v_ashrrev_i32_e32 v5, 31, v4
	s_barrier
	v_lshl_add_u64 v[6:7], s[2:3], 0, v[2:3]
	v_mov_b32_e32 v65, 0
	v_lshlrev_b64 v[4:5], 11, v[4:5]
	v_lshl_add_u64 v[2:3], s[0:1], 0, v[2:3]
	v_lshlrev_b32_e32 v1, 4, v1
	v_lshl_add_u64 v[70:71], v[2:3], 0, v[64:65]
	v_lshl_add_u64 v[2:3], s[0:1], 0, v[4:5]
	v_and_b32_e32 v1, 0xfffffc00, v1
	v_lshl_add_u64 v[72:73], v[2:3], 0, v[64:65]
	v_readfirstlane_b32 s0, v1
	v_add_u32_e32 v2, 0x1000, v1
	v_lshl_add_u64 v[66:67], v[6:7], 0, v[64:65]
	v_lshl_add_u64 v[6:7], s[2:3], 0, v[4:5]
	s_mov_b32 m0, s0
	v_readfirstlane_b32 s0, v2
	v_add_u32_e32 v2, 0x2000, v1
	v_lshl_add_u64 v[68:69], v[6:7], 0, v[64:65]
	s_mov_b32 m0, s0
	v_readfirstlane_b32 s0, v2
	v_add_u32_e32 v1, 0x3000, v1
	s_mov_b32 m0, s0
	v_readfirstlane_b32 s0, v1
	s_mov_b32 m0, s0
	v_mov_b32_e32 v1, v220
	v_lshl_add_u64 v[2:3], v[66:67], 0, 64
	v_lshlrev_b32_e32 v1, 4, v1
	v_and_b32_e32 v1, 0xfffffc00, v1
	v_add_u32_e32 v4, 0x4000, v1
	v_and_b32_e32 v74, 64, v0
	v_readfirstlane_b32 s0, v4
	v_add_u32_e32 v4, 0x5000, v1
	s_mov_b32 m0, s0
	v_readfirstlane_b32 s0, v4
	v_add_u32_e32 v4, 0x6000, v1
	v_lshl_add_u64 v[2:3], v[68:69], 0, 64
	s_mov_b32 m0, s0
	v_readfirstlane_b32 s0, v4
	v_add_u32_e32 v1, 0x7000, v1
	v_lshl_add_u64 v[2:3], v[70:71], 0, 64
	s_mov_b32 m0, s0
	v_readfirstlane_b32 s0, v1
	v_lshl_add_u64 v[2:3], v[72:73], 0, 64
	s_mov_b32 m0, s0
	v_ashrrev_i32_e32 v0, 1, v0
	v_readlane_b32 s4, v228, 6
	v_readlane_b32 s5, v228, 7
	v_and_b32_e32 v75, 0xffffffc0, v0
	s_add_u32 s0, s6, 0x8140000
	v_or_b32_e32 v76, 16, v75
	v_or_b32_e32 v77, 20, v75
	v_or_b32_e32 v78, 24, v75
	v_or_b32_e32 v79, 28, v75
	v_or_b32_e32 v80, 32, v75
	v_or_b32_e32 v81, 36, v75
	v_or_b32_e32 v82, 40, v75
	v_or_b32_e32 v83, 44, v75
	v_or_b32_e32 v84, 48, v75
	v_or_b32_e32 v85, 52, v75
	v_or_b32_e32 v86, 56, v75
	v_or_b32_e32 v87, 60, v75
	s_addc_u32 s1, s7, 0
	s_mov_b32 s14, 0x3ffffc0
	s_movk_i32 s15, 0x13c0
	s_mov_b64 s[2:3], 0x80
	s_mov_b64 s[4:5], 0xc0
	s_mov_b64 s[6:7], 0x100
	s_movk_i32 s16, 0x1100
	s_movk_i32 s17, 0x440
	s_movk_i32 s18, 0xb10
	s_movk_i32 s19, 0x110
	s_movk_i32 s20, 0x1620
	s_mov_b32 s21, s8
	v_readlane_b32 s9, v228, 1
	v_lshrrev_b32_e32 v133, 3, v220
	v_lshlrev_b32_e32 v133, 11, v133
	v_bfe_u32 v134, v220, 4, 3
	v_and_b32_e32 v135, 7, v220
	v_xor_b32_e32 v134, v134, v135
	v_lshl_add_u32 v133, v134, 4, v133
	v_add_u32_e32 v134, 0x10000, v133
	v_add_u32_e32 v135, 0x20000, v133
	v_add_u32_e32 v136, 0x30000, v133
	v_and_b32_e32 v143, 15, v220
	v_bfe_u32 v144, v220, 4, 2
	v_bfe_u32 v145, v220, 1, 3
	v_xor_b32_e32 v144, v144, v145
	v_lshlrev_b32_e32 v144, 4, v144
	v_lshl_add_u32 v143, v143, 7, v144
	v_lshrrev_b32_e32 v144, 7, v220
	v_lshl_add_u32 v137, v144, 13, v143
	v_xor_b32_e32 v138, 64, v137
	v_bfe_u32 v144, v220, 6, 1
	v_lshl_add_u32 v139, v144, 13, v143
	v_add_u32_e32 v139, 0x4000, v139
	v_xor_b32_e32 v140, 64, v139
	v_lshl_add_u32 v141, v144, 10, v139
	v_lshl_add_u32 v142, v144, 10, v140
	v_readfirstlane_b32 s92, v220
	s_nop 0
	s_lshl_b32 s92, s92, 4
	s_add_u32 s93, s92, 0x8000
	s_mov_b32 m0, s92
	s_nop 0
	global_load_lds_dwordx4 v133, s[88:89]
	s_add_u32 m0, m0, 0x1000
	s_nop 0
	global_load_lds_dwordx4 v134, s[88:89]
	s_add_u32 m0, m0, 0x1000
	s_nop 0
	global_load_lds_dwordx4 v135, s[88:89]
	s_add_u32 m0, m0, 0x1000
	s_nop 0
	global_load_lds_dwordx4 v136, s[88:89]
	s_add_u32 m0, m0, 0x1000
	s_nop 0
	global_load_lds_dwordx4 v133, s[90:91]
	s_add_u32 m0, m0, 0x1000
	s_nop 0
	global_load_lds_dwordx4 v134, s[90:91]
	s_add_u32 m0, m0, 0x1000
	s_nop 0
	global_load_lds_dwordx4 v135, s[90:91]
	s_add_u32 m0, m0, 0x1000
	s_nop 0
	global_load_lds_dwordx4 v136, s[90:91]
	s_branch .LBB0_74

; __device__ __forceinline__ int tid_() { int t = threadIdx.x; asm volatile("" : "+v"(t)); return t; }
; __device__ __forceinline__ f32x4 mfma16(bf16x8 a, bf16x8 b, f32x4 c) { return __builtin_amdgcn_mfma_f32_16x16x32_bf16(a, b, c, 0, 0, 0); }
; #define RAW_BARRIER() do { asm volatile("s_waitcnt lgkmcnt(0)" ::: "memory"); __builtin_amdgcn_s_barrier(); } while (0)
; #define GEMM_STEP(J, BUF, NBUF) do { asm volatile("s_waitcnt vmcnt(4)" ::: "memory"); RAW_BARRIER(); \
;     if ((J) + 2 < nk) gemm_issue(g, (J) + 2, NBUF, L); comp(BUF); } while (0)
; __device__ __forceinline__ void gemm_main(f32x4 (&acc)[4][4], const GemmOps& g, int K, u16* lds) {
;   const int tid = tid_(), lane = tid & 63, wid = tid >> 6;
;   const int wm = wid >> 1, wn = wid & 1, fr = lane & 15, fq = lane >> 4;
;   char* L = (char*)lds;
;   int offA[4], offB[4];
; #pragma unroll
;   for (int i = 0; i < 4; ++i) {
;     const int Ra = wm * 64 + i * 16 + fr, Rb = wn * 64 + i * 16 + fr;
;     offA[i] = Ra * 64 + ((fq ^ ((Ra >> 2) & 3)) << 4);
;     offB[i] = 8192 + Rb * 64 + ((fq ^ ((Rb >> 2) & 3)) << 4);
;   }
;   auto comp = [&](int buf) __attribute__((always_inline)) {
;     const char* sb = L + buf * GEMM_STAGE_B;
;     bf16x8 a[4], b[4];
; #pragma unroll
;     for (int i = 0; i < 4; ++i) a[i] = *(const bf16x8*)(sb + offA[i]);
; #pragma unroll
;     for (int j = 0; j < 4; ++j) b[j] = *(const bf16x8*)(sb + offB[j]);
; #pragma unroll
;     for (int i = 0; i < 4; ++i)
; #pragma unroll
;       for (int j = 0; j < 4; ++j) acc[i][j] = mfma16(a[i], b[j], acc[i][j]);
;   };
;   const int nk = K >> 5;
;     ...
;   int j = 0;
;   for (; j + 3 <= nk - 1; j += 3) {
;     GEMM_STEP(j, 0, 2);
;     GEMM_STEP(j + 1, 1, 0);
;     GEMM_STEP(j + 2, 2, 1);
;   }
;   GEMM_STEP(j, 0, 2);
;   asm volatile("s_waitcnt vmcnt(0)" ::: "memory");
;   RAW_BARRIER();
;   comp(1);
;     ...
; }
; __device__ __forceinline__ void zero_acc(f32x4 (&acc)[4][4]) {
; #pragma unroll
;   for (int i = 0; i < 4; ++i)
; #pragma unroll
;     for (int j = 0; j < 4; ++j) acc[i][j] = f32x4{0.f, 0.f, 0.f, 0.f};
; }
.LBB0_75:
	v_mov_b32_e32 v48, 0
	v_mov_b32_e32 v49, 0
	v_mov_b32_e32 v50, 0
	v_mov_b32_e32 v51, 0
	v_mov_b32_e32 v56, 0
	v_mov_b32_e32 v57, 0
	v_mov_b32_e32 v58, 0
	v_mov_b32_e32 v59, 0
	v_mov_b32_e32 v52, 0
	v_mov_b32_e32 v53, 0
	v_mov_b32_e32 v54, 0
	v_mov_b32_e32 v55, 0
	v_mov_b32_e32 v60, 0
	v_mov_b32_e32 v61, 0
	v_mov_b32_e32 v62, 0
	v_mov_b32_e32 v63, 0
	v_mov_b32_e32 v40, 0
	v_mov_b32_e32 v41, 0
	v_mov_b32_e32 v42, 0
	v_mov_b32_e32 v43, 0
	v_mov_b32_e32 v44, 0
	v_mov_b32_e32 v45, 0
	v_mov_b32_e32 v46, 0
	v_mov_b32_e32 v47, 0
	v_mov_b32_e32 v32, 0
	v_mov_b32_e32 v33, 0
	v_mov_b32_e32 v34, 0
	v_mov_b32_e32 v35, 0
	v_mov_b32_e32 v36, 0
	v_mov_b32_e32 v37, 0
	v_mov_b32_e32 v38, 0
	v_mov_b32_e32 v39, 0
	v_mov_b32_e32 v24, 0
	v_mov_b32_e32 v25, 0
	v_mov_b32_e32 v26, 0
	v_mov_b32_e32 v27, 0
	v_mov_b32_e32 v28, 0
	v_mov_b32_e32 v29, 0
	v_mov_b32_e32 v30, 0
	v_mov_b32_e32 v31, 0
	v_mov_b32_e32 v16, 0
	v_mov_b32_e32 v17, 0
	v_mov_b32_e32 v18, 0
	v_mov_b32_e32 v19, 0
	v_mov_b32_e32 v20, 0
	v_mov_b32_e32 v21, 0
	v_mov_b32_e32 v22, 0
	v_mov_b32_e32 v23, 0
	v_mov_b32_e32 v0, 0
	v_mov_b32_e32 v1, 0
	v_mov_b32_e32 v2, 0
	v_mov_b32_e32 v3, 0
	v_mov_b32_e32 v4, 0
	v_mov_b32_e32 v5, 0
	v_mov_b32_e32 v6, 0
	v_mov_b32_e32 v7, 0
	v_mov_b32_e32 v8, 0
	v_mov_b32_e32 v9, 0
	v_mov_b32_e32 v10, 0
	v_mov_b32_e32 v11, 0
	v_mov_b32_e32 v12, 0
	v_mov_b32_e32 v13, 0
	v_mov_b32_e32 v14, 0
	v_mov_b32_e32 v15, 0
	s_mov_b32 s94, 7
.Lg1_k:
	s_waitcnt vmcnt(0)
	s_barrier
	s_add_u32 s88, s88, 0x80
	s_addc_u32 s89, s89, 0
	s_add_u32 s90, s90, 0x80
	s_addc_u32 s91, s91, 0
	s_mov_b32 m0, s93
	ds_read_b128 v[148:151], v137 offset:0
	global_load_lds_dwordx4 v133, s[88:89]
	s_add_u32 m0, m0, 0x1000
	ds_read_b128 v[152:155], v137 offset:2048
	global_load_lds_dwordx4 v134, s[88:89]
	s_add_u32 m0, m0, 0x1000
	ds_read_b128 v[156:159], v137 offset:4096
	global_load_lds_dwordx4 v135, s[88:89]
	s_add_u32 m0, m0, 0x1000
	ds_read_b128 v[160:163], v137 offset:6144
	global_load_lds_dwordx4 v136, s[88:89]
	s_add_u32 m0, m0, 0x1000
	ds_read_b128 v[180:183], v139 offset:0
	global_load_lds_dwordx4 v133, s[90:91]
	s_add_u32 m0, m0, 0x1000
	ds_read_b128 v[184:187], v139 offset:2048
	global_load_lds_dwordx4 v134, s[90:91]
	s_add_u32 m0, m0, 0x1400
	ds_read_b128 v[188:191], v139 offset:4096
	global_load_lds_dwordx4 v135, s[90:91]
	s_add_u32 m0, m0, 0x1000
	ds_read_b128 v[192:195], v139 offset:6144
	global_load_lds_dwordx4 v136, s[90:91]
	ds_read_b128 v[164:167], v138 offset:0
	ds_read_b128 v[168:171], v138 offset:2048
	ds_read_b128 v[172:175], v138 offset:4096
	ds_read_b128 v[176:179], v138 offset:6144
	ds_read_b128 v[196:199], v140 offset:0
	ds_read_b128 v[200:203], v140 offset:2048
	ds_read_b128 v[204:207], v140 offset:4096
	ds_read_b128 v[208:211], v140 offset:6144
	s_waitcnt lgkmcnt(8)
	v_mfma_f32_16x16x32_bf16 v[48:51], v[148:151], v[180:183], v[48:51]
	v_mfma_f32_16x16x32_bf16 v[56:59], v[148:151], v[184:187], v[56:59]
	v_mfma_f32_16x16x32_bf16 v[52:55], v[148:151], v[188:191], v[52:55]
	v_mfma_f32_16x16x32_bf16 v[60:63], v[148:151], v[192:195], v[60:63]
	v_mfma_f32_16x16x32_bf16 v[40:43], v[152:155], v[180:183], v[40:43]
	v_mfma_f32_16x16x32_bf16 v[44:47], v[152:155], v[184:187], v[44:47]
	v_mfma_f32_16x16x32_bf16 v[32:35], v[152:155], v[188:191], v[32:35]
	v_mfma_f32_16x16x32_bf16 v[36:39], v[152:155], v[192:195], v[36:39]
	v_mfma_f32_16x16x32_bf16 v[24:27], v[156:159], v[180:183], v[24:27]
	v_mfma_f32_16x16x32_bf16 v[28:31], v[156:159], v[184:187], v[28:31]
	v_mfma_f32_16x16x32_bf16 v[16:19], v[156:159], v[188:191], v[16:19]
	v_mfma_f32_16x16x32_bf16 v[20:23], v[156:159], v[192:195], v[20:23]
	v_mfma_f32_16x16x32_bf16 v[0:3], v[160:163], v[180:183], v[0:3]
	v_mfma_f32_16x16x32_bf16 v[4:7], v[160:163], v[184:187], v[4:7]
	v_mfma_f32_16x16x32_bf16 v[8:11], v[160:163], v[188:191], v[8:11]
	v_mfma_f32_16x16x32_bf16 v[12:15], v[160:163], v[192:195], v[12:15]
	s_waitcnt lgkmcnt(0)
	v_mfma_f32_16x16x32_bf16 v[48:51], v[164:167], v[196:199], v[48:51]
	v_mfma_f32_16x16x32_bf16 v[56:59], v[164:167], v[200:203], v[56:59]
	v_mfma_f32_16x16x32_bf16 v[52:55], v[164:167], v[204:207], v[52:55]
	v_mfma_f32_16x16x32_bf16 v[60:63], v[164:167], v[208:211], v[60:63]
	v_mfma_f32_16x16x32_bf16 v[40:43], v[168:171], v[196:199], v[40:43]
	v_mfma_f32_16x16x32_bf16 v[44:47], v[168:171], v[200:203], v[44:47]
	v_mfma_f32_16x16x32_bf16 v[32:35], v[168:171], v[204:207], v[32:35]
	v_mfma_f32_16x16x32_bf16 v[36:39], v[168:171], v[208:211], v[36:39]
	v_mfma_f32_16x16x32_bf16 v[24:27], v[172:175], v[196:199], v[24:27]
	v_mfma_f32_16x16x32_bf16 v[28:31], v[172:175], v[200:203], v[28:31]
	v_mfma_f32_16x16x32_bf16 v[16:19], v[172:175], v[204:207], v[16:19]
	v_mfma_f32_16x16x32_bf16 v[20:23], v[172:175], v[208:211], v[20:23]
	v_mfma_f32_16x16x32_bf16 v[0:3], v[176:179], v[196:199], v[0:3]
	v_mfma_f32_16x16x32_bf16 v[4:7], v[176:179], v[200:203], v[4:7]
	v_mfma_f32_16x16x32_bf16 v[8:11], v[176:179], v[204:207], v[8:11]
	v_mfma_f32_16x16x32_bf16 v[12:15], v[176:179], v[208:211], v[12:15]
	s_waitcnt vmcnt(0)
	s_barrier
; __device__ __forceinline__ int tid_() { int t = threadIdx.x; asm volatile("" : "+v"(t)); return t; }
; __device__ __forceinline__ f32x4 mfma16(bf16x8 a, bf16x8 b, f32x4 c) { return __builtin_amdgcn_mfma_f32_16x16x32_bf16(a, b, c, 0, 0, 0); }
; #define RAW_BARRIER() do { asm volatile("s_waitcnt lgkmcnt(0)" ::: "memory"); __builtin_amdgcn_s_barrier(); } while (0)
; #define GEMM_STEP(J, BUF, NBUF) do { asm volatile("s_waitcnt vmcnt(4)" ::: "memory"); RAW_BARRIER(); \
;     if ((J) + 2 < nk) gemm_issue(g, (J) + 2, NBUF, L); comp(BUF); } while (0)
; __device__ __forceinline__ void gemm_main(f32x4 (&acc)[4][4], const GemmOps& g, int K, u16* lds) {
;   const int tid = tid_(), lane = tid & 63, wid = tid >> 6;
;   const int wm = wid >> 1, wn = wid & 1, fr = lane & 15, fq = lane >> 4;
;   char* L = (char*)lds;
;   int offA[4], offB[4];
; #pragma unroll
;   for (int i = 0; i < 4; ++i) {
;     const int Ra = wm * 64 + i * 16 + fr, Rb = wn * 64 + i * 16 + fr;
;     offA[i] = Ra * 64 + ((fq ^ ((Ra >> 2) & 3)) << 4);
;     offB[i] = 8192 + Rb * 64 + ((fq ^ ((Rb >> 2) & 3)) << 4);
;   }
;   auto comp = [&](int buf) __attribute__((always_inline)) {
;     const char* sb = L + buf * GEMM_STAGE_B;
;     bf16x8 a[4], b[4];
; #pragma unroll
;     for (int i = 0; i < 4; ++i) a[i] = *(const bf16x8*)(sb + offA[i]);
; #pragma unroll
;     for (int j = 0; j < 4; ++j) b[j] = *(const bf16x8*)(sb + offB[j]);
; #pragma unroll
;     for (int i = 0; i < 4; ++i)
; #pragma unroll
;       for (int j = 0; j < 4; ++j) acc[i][j] = mfma16(a[i], b[j], acc[i][j]);
;   };
;   const int nk = K >> 5;
;     ...
;   int j = 0;
;   for (; j + 3 <= nk - 1; j += 3) {
;     GEMM_STEP(j, 0, 2);
;     GEMM_STEP(j + 1, 1, 0);
;     GEMM_STEP(j + 2, 2, 1);
;   }
;   GEMM_STEP(j, 0, 2);
;   asm volatile("s_waitcnt vmcnt(0)" ::: "memory");
;   RAW_BARRIER();
;   comp(1);
	s_add_u32 s88, s88, 0x80
	s_addc_u32 s89, s89, 0
	s_add_u32 s90, s90, 0x80
	s_addc_u32 s91, s91, 0
	s_mov_b32 m0, s92
	ds_read_b128 v[148:151], v137 offset:32768
	global_load_lds_dwordx4 v133, s[88:89]
	s_add_u32 m0, m0, 0x1000
	ds_read_b128 v[152:155], v137 offset:34816
	global_load_lds_dwordx4 v134, s[88:89]
	s_add_u32 m0, m0, 0x1000
	ds_read_b128 v[156:159], v137 offset:36864
	global_load_lds_dwordx4 v135, s[88:89]
	s_add_u32 m0, m0, 0x1000
	ds_read_b128 v[160:163], v137 offset:38912
	global_load_lds_dwordx4 v136, s[88:89]
	s_add_u32 m0, m0, 0x1000
	ds_read_b128 v[180:183], v141 offset:32768
	global_load_lds_dwordx4 v133, s[90:91]
	s_add_u32 m0, m0, 0x1000
	ds_read_b128 v[184:187], v141 offset:34816
	global_load_lds_dwordx4 v134, s[90:91]
	s_add_u32 m0, m0, 0x1000
	ds_read_b128 v[188:191], v141 offset:36864
	global_load_lds_dwordx4 v135, s[90:91]
	s_add_u32 m0, m0, 0x1000
	ds_read_b128 v[192:195], v141 offset:38912
	global_load_lds_dwordx4 v136, s[90:91]
	ds_read_b128 v[164:167], v138 offset:32768
	ds_read_b128 v[168:171], v138 offset:34816
	ds_read_b128 v[172:175], v138 offset:36864
	ds_read_b128 v[176:179], v138 offset:38912
	ds_read_b128 v[196:199], v142 offset:32768
	ds_read_b128 v[200:203], v142 offset:34816
	ds_read_b128 v[204:207], v142 offset:36864
	ds_read_b128 v[208:211], v142 offset:38912
	s_waitcnt lgkmcnt(8)
	v_mfma_f32_16x16x32_bf16 v[48:51], v[148:151], v[180:183], v[48:51]
	v_mfma_f32_16x16x32_bf16 v[56:59], v[148:151], v[184:187], v[56:59]
	v_mfma_f32_16x16x32_bf16 v[52:55], v[148:151], v[188:191], v[52:55]
	v_mfma_f32_16x16x32_bf16 v[60:63], v[148:151], v[192:195], v[60:63]
	v_mfma_f32_16x16x32_bf16 v[40:43], v[152:155], v[180:183], v[40:43]
	v_mfma_f32_16x16x32_bf16 v[44:47], v[152:155], v[184:187], v[44:47]
	v_mfma_f32_16x16x32_bf16 v[32:35], v[152:155], v[188:191], v[32:35]
	v_mfma_f32_16x16x32_bf16 v[36:39], v[152:155], v[192:195], v[36:39]
	v_mfma_f32_16x16x32_bf16 v[24:27], v[156:159], v[180:183], v[24:27]
	v_mfma_f32_16x16x32_bf16 v[28:31], v[156:159], v[184:187], v[28:31]
	v_mfma_f32_16x16x32_bf16 v[16:19], v[156:159], v[188:191], v[16:19]
	v_mfma_f32_16x16x32_bf16 v[20:23], v[156:159], v[192:195], v[20:23]
	v_mfma_f32_16x16x32_bf16 v[0:3], v[160:163], v[180:183], v[0:3]
	v_mfma_f32_16x16x32_bf16 v[4:7], v[160:163], v[184:187], v[4:7]
	v_mfma_f32_16x16x32_bf16 v[8:11], v[160:163], v[188:191], v[8:11]
	v_mfma_f32_16x16x32_bf16 v[12:15], v[160:163], v[192:195], v[12:15]
	s_waitcnt lgkmcnt(0)
	v_mfma_f32_16x16x32_bf16 v[48:51], v[164:167], v[196:199], v[48:51]
	v_mfma_f32_16x16x32_bf16 v[56:59], v[164:167], v[200:203], v[56:59]
	v_mfma_f32_16x16x32_bf16 v[52:55], v[164:167], v[204:207], v[52:55]
	v_mfma_f32_16x16x32_bf16 v[60:63], v[164:167], v[208:211], v[60:63]
	v_mfma_f32_16x16x32_bf16 v[40:43], v[168:171], v[196:199], v[40:43]
	v_mfma_f32_16x16x32_bf16 v[44:47], v[168:171], v[200:203], v[44:47]
	v_mfma_f32_16x16x32_bf16 v[32:35], v[168:171], v[204:207], v[32:35]
	v_mfma_f32_16x16x32_bf16 v[36:39], v[168:171], v[208:211], v[36:39]
	v_mfma_f32_16x16x32_bf16 v[24:27], v[172:175], v[196:199], v[24:27]
	v_mfma_f32_16x16x32_bf16 v[28:31], v[172:175], v[200:203], v[28:31]
	v_mfma_f32_16x16x32_bf16 v[16:19], v[172:175], v[204:207], v[16:19]
	v_mfma_f32_16x16x32_bf16 v[20:23], v[172:175], v[208:211], v[20:23]
	v_mfma_f32_16x16x32_bf16 v[0:3], v[176:179], v[196:199], v[0:3]
	v_mfma_f32_16x16x32_bf16 v[4:7], v[176:179], v[200:203], v[4:7]
	v_mfma_f32_16x16x32_bf16 v[8:11], v[176:179], v[204:207], v[8:11]
	v_mfma_f32_16x16x32_bf16 v[12:15], v[176:179], v[208:211], v[12:15]
	s_sub_u32 s94, s94, 1
	s_cmp_lg_u32 s94, 0
	s_cbranch_scc1 .Lg1_k
	s_waitcnt vmcnt(0)
	s_barrier
	s_add_u32 s88, s88, 0x80
	s_addc_u32 s89, s89, 0
	s_add_u32 s90, s90, 0x80
	s_addc_u32 s91, s91, 0
	s_mov_b32 m0, s93
	ds_read_b128 v[148:151], v137 offset:0
	global_load_lds_dwordx4 v133, s[88:89]
	s_add_u32 m0, m0, 0x1000
	ds_read_b128 v[152:155], v137 offset:2048
	global_load_lds_dwordx4 v134, s[88:89]
	s_add_u32 m0, m0, 0x1000
	ds_read_b128 v[156:159], v137 offset:4096
	global_load_lds_dwordx4 v135, s[88:89]
	s_add_u32 m0, m0, 0x1000
	ds_read_b128 v[160:163], v137 offset:6144
	global_load_lds_dwordx4 v136, s[88:89]
	s_add_u32 m0, m0, 0x1000
	ds_read_b128 v[180:183], v139 offset:0
	global_load_lds_dwordx4 v133, s[90:91]
	s_add_u32 m0, m0, 0x1000
	ds_read_b128 v[184:187], v139 offset:2048
	global_load_lds_dwordx4 v134, s[90:91]
	s_add_u32 m0, m0, 0x1400
	ds_read_b128 v[188:191], v139 offset:4096
	global_load_lds_dwordx4 v135, s[90:91]
	s_add_u32 m0, m0, 0x1000
	ds_read_b128 v[192:195], v139 offset:6144
	global_load_lds_dwordx4 v136, s[90:91]
	ds_read_b128 v[164:167], v138 offset:0
	ds_read_b128 v[168:171], v138 offset:2048
	ds_read_b128 v[172:175], v138 offset:4096
	ds_read_b128 v[176:179], v138 offset:6144
	ds_read_b128 v[196:199], v140 offset:0
	ds_read_b128 v[200:203], v140 offset:2048
	ds_read_b128 v[204:207], v140 offset:4096
	ds_read_b128 v[208:211], v140 offset:6144
	s_waitcnt lgkmcnt(8)
	v_mfma_f32_16x16x32_bf16 v[48:51], v[148:151], v[180:183], v[48:51]
	v_mfma_f32_16x16x32_bf16 v[56:59], v[148:151], v[184:187], v[56:59]
	v_mfma_f32_16x16x32_bf16 v[52:55], v[148:151], v[188:191], v[52:55]
	v_mfma_f32_16x16x32_bf16 v[60:63], v[148:151], v[192:195], v[60:63]
	v_mfma_f32_16x16x32_bf16 v[40:43], v[152:155], v[180:183], v[40:43]
	v_mfma_f32_16x16x32_bf16 v[44:47], v[152:155], v[184:187], v[44:47]
	v_mfma_f32_16x16x32_bf16 v[32:35], v[152:155], v[188:191], v[32:35]
	v_mfma_f32_16x16x32_bf16 v[36:39], v[152:155], v[192:195], v[36:39]
	v_mfma_f32_16x16x32_bf16 v[24:27], v[156:159], v[180:183], v[24:27]
	v_mfma_f32_16x16x32_bf16 v[28:31], v[156:159], v[184:187], v[28:31]
	v_mfma_f32_16x16x32_bf16 v[16:19], v[156:159], v[188:191], v[16:19]
	v_mfma_f32_16x16x32_bf16 v[20:23], v[156:159], v[192:195], v[20:23]
	v_mfma_f32_16x16x32_bf16 v[0:3], v[160:163], v[180:183], v[0:3]
	v_mfma_f32_16x16x32_bf16 v[4:7], v[160:163], v[184:187], v[4:7]
	v_mfma_f32_16x16x32_bf16 v[8:11], v[160:163], v[188:191], v[8:11]
	v_mfma_f32_16x16x32_bf16 v[12:15], v[160:163], v[192:195], v[12:15]
	s_waitcnt lgkmcnt(0)
; __device__ __forceinline__ f32x4 mfma16(bf16x8 a, bf16x8 b, f32x4 c) { return __builtin_amdgcn_mfma_f32_16x16x32_bf16(a, b, c, 0, 0, 0); }
; #define RAW_BARRIER() do { asm volatile("s_waitcnt lgkmcnt(0)" ::: "memory"); __builtin_amdgcn_s_barrier(); } while (0)
; #define GEMM_STEP(J, BUF, NBUF) do { asm volatile("s_waitcnt vmcnt(4)" ::: "memory"); RAW_BARRIER(); \
;     if ((J) + 2 < nk) gemm_issue(g, (J) + 2, NBUF, L); comp(BUF); } while (0)
; __device__ __forceinline__ void gemm_main(f32x4 (&acc)[4][4], const GemmOps& g, int K, u16* lds) {
;     ...
;   auto comp = [&](int buf) __attribute__((always_inline)) {
;     const char* sb = L + buf * GEMM_STAGE_B;
;     bf16x8 a[4], b[4];
; #pragma unroll
;     for (int i = 0; i < 4; ++i) a[i] = *(const bf16x8*)(sb + offA[i]);
; #pragma unroll
;     for (int j = 0; j < 4; ++j) b[j] = *(const bf16x8*)(sb + offB[j]);
; #pragma unroll
;     for (int i = 0; i < 4; ++i)
; #pragma unroll
;       for (int j = 0; j < 4; ++j) acc[i][j] = mfma16(a[i], b[j], acc[i][j]);
;   };
;   const int nk = K >> 5;
;     ...
;   int j = 0;
;   for (; j + 3 <= nk - 1; j += 3) {
;     GEMM_STEP(j, 0, 2);
;     GEMM_STEP(j + 1, 1, 0);
;     GEMM_STEP(j + 2, 2, 1);
;   }
;   GEMM_STEP(j, 0, 2);
;   asm volatile("s_waitcnt vmcnt(0)" ::: "memory");
;   RAW_BARRIER();
;   comp(1);
	v_mfma_f32_16x16x32_bf16 v[48:51], v[164:167], v[196:199], v[48:51]
	v_mfma_f32_16x16x32_bf16 v[56:59], v[164:167], v[200:203], v[56:59]
	v_mfma_f32_16x16x32_bf16 v[52:55], v[164:167], v[204:207], v[52:55]
	v_mfma_f32_16x16x32_bf16 v[60:63], v[164:167], v[208:211], v[60:63]
	v_mfma_f32_16x16x32_bf16 v[40:43], v[168:171], v[196:199], v[40:43]
	v_mfma_f32_16x16x32_bf16 v[44:47], v[168:171], v[200:203], v[44:47]
	v_mfma_f32_16x16x32_bf16 v[32:35], v[168:171], v[204:207], v[32:35]
	v_mfma_f32_16x16x32_bf16 v[36:39], v[168:171], v[208:211], v[36:39]
	v_mfma_f32_16x16x32_bf16 v[24:27], v[172:175], v[196:199], v[24:27]
	v_mfma_f32_16x16x32_bf16 v[28:31], v[172:175], v[200:203], v[28:31]
	v_mfma_f32_16x16x32_bf16 v[16:19], v[172:175], v[204:207], v[16:19]
	v_mfma_f32_16x16x32_bf16 v[20:23], v[172:175], v[208:211], v[20:23]
	v_mfma_f32_16x16x32_bf16 v[0:3], v[176:179], v[196:199], v[0:3]
	v_mfma_f32_16x16x32_bf16 v[4:7], v[176:179], v[200:203], v[4:7]
	v_mfma_f32_16x16x32_bf16 v[8:11], v[176:179], v[204:207], v[8:11]
	v_mfma_f32_16x16x32_bf16 v[12:15], v[176:179], v[208:211], v[12:15]
	s_waitcnt vmcnt(0)
	s_barrier
	ds_read_b128 v[148:151], v137 offset:32768
	ds_read_b128 v[152:155], v137 offset:34816
	ds_read_b128 v[156:159], v137 offset:36864
	ds_read_b128 v[160:163], v137 offset:38912
	ds_read_b128 v[180:183], v141 offset:32768
	ds_read_b128 v[184:187], v141 offset:34816
	ds_read_b128 v[188:191], v141 offset:36864
	ds_read_b128 v[192:195], v141 offset:38912
	ds_read_b128 v[164:167], v138 offset:32768
	ds_read_b128 v[168:171], v138 offset:34816
	ds_read_b128 v[172:175], v138 offset:36864
	ds_read_b128 v[176:179], v138 offset:38912
	ds_read_b128 v[196:199], v142 offset:32768
	ds_read_b128 v[200:203], v142 offset:34816
	ds_read_b128 v[204:207], v142 offset:36864
	ds_read_b128 v[208:211], v142 offset:38912
	s_waitcnt lgkmcnt(8)
	v_mfma_f32_16x16x32_bf16 v[48:51], v[148:151], v[180:183], v[48:51]
	v_mfma_f32_16x16x32_bf16 v[56:59], v[148:151], v[184:187], v[56:59]
	v_mfma_f32_16x16x32_bf16 v[52:55], v[148:151], v[188:191], v[52:55]
	v_mfma_f32_16x16x32_bf16 v[60:63], v[148:151], v[192:195], v[60:63]
	v_mfma_f32_16x16x32_bf16 v[40:43], v[152:155], v[180:183], v[40:43]
	v_mfma_f32_16x16x32_bf16 v[44:47], v[152:155], v[184:187], v[44:47]
	v_mfma_f32_16x16x32_bf16 v[32:35], v[152:155], v[188:191], v[32:35]
	v_mfma_f32_16x16x32_bf16 v[36:39], v[152:155], v[192:195], v[36:39]
	v_mfma_f32_16x16x32_bf16 v[24:27], v[156:159], v[180:183], v[24:27]
	v_mfma_f32_16x16x32_bf16 v[28:31], v[156:159], v[184:187], v[28:31]
	v_mfma_f32_16x16x32_bf16 v[16:19], v[156:159], v[188:191], v[16:19]
	v_mfma_f32_16x16x32_bf16 v[20:23], v[156:159], v[192:195], v[20:23]
	v_mfma_f32_16x16x32_bf16 v[0:3], v[160:163], v[180:183], v[0:3]
	v_mfma_f32_16x16x32_bf16 v[4:7], v[160:163], v[184:187], v[4:7]
	v_mfma_f32_16x16x32_bf16 v[8:11], v[160:163], v[188:191], v[8:11]
	v_mfma_f32_16x16x32_bf16 v[12:15], v[160:163], v[192:195], v[12:15]
	s_waitcnt lgkmcnt(0)
	v_mfma_f32_16x16x32_bf16 v[48:51], v[164:167], v[196:199], v[48:51]
	v_mfma_f32_16x16x32_bf16 v[56:59], v[164:167], v[200:203], v[56:59]
	v_mfma_f32_16x16x32_bf16 v[52:55], v[164:167], v[204:207], v[52:55]
	v_mfma_f32_16x16x32_bf16 v[60:63], v[164:167], v[208:211], v[60:63]
	v_mfma_f32_16x16x32_bf16 v[40:43], v[168:171], v[196:199], v[40:43]
	v_mfma_f32_16x16x32_bf16 v[44:47], v[168:171], v[200:203], v[44:47]
	v_mfma_f32_16x16x32_bf16 v[32:35], v[168:171], v[204:207], v[32:35]
	v_mfma_f32_16x16x32_bf16 v[36:39], v[168:171], v[208:211], v[36:39]
	v_mfma_f32_16x16x32_bf16 v[24:27], v[172:175], v[196:199], v[24:27]
	v_mfma_f32_16x16x32_bf16 v[28:31], v[172:175], v[200:203], v[28:31]
	v_mfma_f32_16x16x32_bf16 v[16:19], v[172:175], v[204:207], v[16:19]
	v_mfma_f32_16x16x32_bf16 v[20:23], v[172:175], v[208:211], v[20:23]
	v_mfma_f32_16x16x32_bf16 v[0:3], v[176:179], v[196:199], v[0:3]
	v_mfma_f32_16x16x32_bf16 v[4:7], v[176:179], v[200:203], v[4:7]
	v_mfma_f32_16x16x32_bf16 v[8:11], v[176:179], v[204:207], v[8:11]
	v_mfma_f32_16x16x32_bf16 v[12:15], v[176:179], v[208:211], v[12:15]
	s_waitcnt lgkmcnt(0)
	s_barrier
; __device__ __forceinline__ int tid_() { int t = threadIdx.x; asm volatile("" : "+v"(t)); return t; }
; __device__ __forceinline__ GemmOps gemm_ops(const u16* A, int lda, const u16* B, int ldb) {
;   const int lane = tid_() & 63, wid = tid_() >> 6, rr = lane >> 2, c = lane & 3;
;   const int R0 = wid * 16 + rr, R1 = (wid + 4) * 16 + rr;
;   GemmOps g;
;   g.a0 = A + (size_t)R0 * lda + ((c ^ ((R0 >> 2) & 3)) << 3);
;   g.a1 = A + (size_t)R1 * lda + ((c ^ ((R1 >> 2) & 3)) << 3);
;   g.b0 = B + (size_t)R0 * ldb + ((c ^ ((R0 >> 2) & 3)) << 3);
;   g.b1 = B + (size_t)R1 * ldb + ((c ^ ((R1 >> 2) & 3)) << 3);
;   return g;
; }
; __device__ __forceinline__ void gemm_issue(const GemmOps& g, int kt, int buf, char* L) {
;   const int wid = tid_() >> 6;
;   char* sb = L + buf * GEMM_STAGE_B;
;   __builtin_amdgcn_global_load_lds((const unsigned*)(g.a0 + kt * 32), (unsigned*)(sb + wid * 1024), 16, 0, 0);
;   __builtin_amdgcn_global_load_lds((const unsigned*)(g.a1 + kt * 32), (unsigned*)(sb + (wid + 4) * 1024), 16, 0, 0);
;   __builtin_amdgcn_global_load_lds((const unsigned*)(g.b0 + kt * 32), (unsigned*)(sb + 8192 + wid * 1024), 16, 0, 0);
;   __builtin_amdgcn_global_load_lds((const unsigned*)(g.b1 + kt * 32), (unsigned*)(sb + 8192 + (wid + 4) * 1024), 16, 0, 0);
; }
; __device__ __forceinline__ void gemm_prologue(const GemmOps& g, u16* lds) {
;   gemm_issue(g, 0, 0, (char*)lds); gemm_issue(g, 1, 1, (char*)lds);
; }
; __device__ void ph_gemm1(const P& p, u16* lds) {
;     ...
;     const int itn = it + gridDim.x; const bool more = itn < NTILES;
;     __syncthreads();
;     if (more) { g = ops(itn); gemm_prologue(g, lds); }
	s_nop 7
	v_readlane_b32 s8, v228, 10
	s_add_i32 s21, s10, s8
	v_readlane_b32 s9, v228, 11
	s_cmpk_gt_i32 s21, 0x17b7
	s_cselect_b64 s[8:9], -1, 0
	s_and_b64 vcc, exec, s[8:9]
	s_cbranch_vccnz .LBB0_78
	s_and_b32 s81, s21, 7
	s_lshr_b32 s82, s21, 3
	s_mul_hi_u32 s83, s82, 0x1642c86
	s_mul_i32 s84, s83, 184
	s_sub_u32 s84, s82, s84
	s_cmp_lt_u32 s83, 4
	s_cselect_b32 s85, 3, 0
	s_cselect_b32 s86, 7, 0
	s_lshr_b32 s87, s84, s85
	s_and_b32 s84, s84, s86
	s_lshl_b32 s83, s83, 3
	s_add_u32 s83, s83, s84
	s_mul_i32 s81, s81, 33
	s_add_u32 s81, s81, s83
	s_mul_i32 s81, s81, 23
	s_add_u32 s80, s81, s87
	s_mul_hi_i32 s11, s80, 0xb21642c9
	s_add_i32 s11, s11, s80
	s_lshr_b32 s22, s11, 31
	s_ashr_i32 s11, s11, 4
	s_add_i32 s22, s11, s22
	s_ashr_i32 s23, s22, 31
	s_lshl_b64 s[24:25], s[22:23], 18
	v_mov_b32_e32 v64, v220
	v_mov_b32_e32 v66, v220
	s_add_u32 s24, s12, s24
	s_mul_i32 s11, s22, 23
	v_readlane_b32 s36, v228, 2
	s_addc_u32 s25, s13, s25
	s_sub_i32 s22, s80, s11
	v_readlane_b32 s40, v228, 6
	v_readlane_b32 s41, v228, 7
	v_lshrrev_b32_e32 v67, 2, v64
	v_ashrrev_i32_e32 v66, 2, v66
	s_ashr_i32 s23, s22, 31
	v_readlane_b32 s42, v228, 8
	v_readlane_b32 s43, v228, 9
	s_mov_b64 s[28:29], s[40:41]
	v_bfi_b32 v66, -16, v66, v67
	s_lshl_b64 s[22:23], s[22:23], 18
	s_mov_b64 s[30:31], s[42:43]
	v_add_u32_e32 v68, 64, v66
	v_lshrrev_b32_e32 v69, 4, v64
	s_add_u32 s22, s30, s22
	v_ashrrev_i32_e32 v67, 31, v66
	v_xor_b32_e32 v64, v69, v64
	v_ashrrev_i32_e32 v69, 31, v68
	s_addc_u32 s23, s31, s23
	s_mov_b64 s[88:89], s[24:25]
	s_mov_b64 s[90:91], s[22:23]
	v_lshlrev_b64 v[70:71], 11, v[66:67]
	v_lshlrev_b32_e32 v64, 4, v64
	v_lshlrev_b64 v[72:73], 11, v[68:69]
	v_lshl_add_u64 v[66:67], s[24:25], 0, v[70:71]
	v_and_b32_e32 v64, 48, v64
	v_lshl_add_u64 v[68:69], s[24:25], 0, v[72:73]
	v_lshl_add_u64 v[70:71], s[22:23], 0, v[70:71]
	v_lshl_add_u64 v[72:73], s[22:23], 0, v[72:73]
	v_lshl_add_u64 v[66:67], v[66:67], 0, v[64:65]
	v_lshl_add_u64 v[68:69], v[68:69], 0, v[64:65]
	v_lshl_add_u64 v[70:71], v[70:71], 0, v[64:65]
	v_lshl_add_u64 v[72:73], v[72:73], 0, v[64:65]
	v_mov_b32_e32 v64, v220
	v_readlane_b32 s37, v228, 3
	v_lshlrev_b32_e32 v64, 4, v64
	v_and_b32_e32 v64, 0xfffffc00, v64
	v_add_u32_e32 v88, 0x1000, v64
	v_readfirstlane_b32 s11, v64
	s_mov_b32 m0, s11
	v_readfirstlane_b32 s11, v88
	v_add_u32_e32 v88, 0x2000, v64
	s_mov_b32 m0, s11
	v_readfirstlane_b32 s11, v88
	v_add_u32_e32 v64, 0x3000, v64
	s_mov_b32 m0, s11
	v_readfirstlane_b32 s11, v64
	s_mov_b32 m0, s11
	v_mov_b32_e32 v64, v220
	v_lshl_add_u64 v[88:89], v[66:67], 0, 64
	v_lshlrev_b32_e32 v64, 4, v64
	v_and_b32_e32 v64, 0xfffffc00, v64
	v_add_u32_e32 v90, 0x4000, v64
	v_readlane_b32 s38, v228, 4
	v_readfirstlane_b32 s11, v90
	v_add_u32_e32 v90, 0x5000, v64
	s_mov_b32 m0, s11
	v_readfirstlane_b32 s11, v90
	v_add_u32_e32 v90, 0x6000, v64
	v_lshl_add_u64 v[88:89], v[68:69], 0, 64
	s_mov_b32 m0, s11
	v_readfirstlane_b32 s11, v90
	v_add_u32_e32 v64, 0x7000, v64
	v_lshl_add_u64 v[88:89], v[70:71], 0, 64
	s_mov_b32 m0, s11
	v_readfirstlane_b32 s11, v64
	v_lshl_add_u64 v[88:89], v[72:73], 0, 64
	s_mov_b32 m0, s11
	v_readlane_b32 s39, v228, 5
	s_mov_b32 m0, s92
	s_nop 0
	global_load_lds_dwordx4 v133, s[88:89]
	s_add_u32 m0, m0, 0x1000
	s_nop 0
	global_load_lds_dwordx4 v134, s[88:89]
	s_add_u32 m0, m0, 0x1000
	s_nop 0
	global_load_lds_dwordx4 v135, s[88:89]
	s_add_u32 m0, m0, 0x1000
	s_nop 0
	global_load_lds_dwordx4 v136, s[88:89]
	s_add_u32 m0, m0, 0x1000
	s_nop 0
	global_load_lds_dwordx4 v133, s[90:91]
	s_add_u32 m0, m0, 0x1000
	s_nop 0
	global_load_lds_dwordx4 v134, s[90:91]
	s_add_u32 m0, m0, 0x1000
	s_nop 0
	global_load_lds_dwordx4 v135, s[90:91]
	s_add_u32 m0, m0, 0x1000
	s_nop 0
	global_load_lds_dwordx4 v136, s[90:91]

; __device__ __forceinline__ int tid_() { int t = threadIdx.x; asm volatile("" : "+v"(t)); return t; }
; __device__ __forceinline__ GemmOps gemm_ops(const u16* A, int lda, const u16* B, int ldb) {
;   const int lane = tid_() & 63, wid = tid_() >> 6, rr = lane >> 2, c = lane & 3;
;   const int R0 = wid * 16 + rr, R1 = (wid + 4) * 16 + rr;
;   GemmOps g;
;   g.a0 = A + (size_t)R0 * lda + ((c ^ ((R0 >> 2) & 3)) << 3);
;   g.a1 = A + (size_t)R1 * lda + ((c ^ ((R1 >> 2) & 3)) << 3);
;   g.b0 = B + (size_t)R0 * ldb + ((c ^ ((R0 >> 2) & 3)) << 3);
;   g.b1 = B + (size_t)R1 * ldb + ((c ^ ((R1 >> 2) & 3)) << 3);
;   return g;
; }
; __device__ __forceinline__ void gemm_issue(const GemmOps& g, int kt, int buf, char* L) {
;   const int wid = tid_() >> 6;
;   char* sb = L + buf * GEMM_STAGE_B;
;   __builtin_amdgcn_global_load_lds((const unsigned*)(g.a0 + kt * 32), (unsigned*)(sb + wid * 1024), 16, 0, 0);
;   __builtin_amdgcn_global_load_lds((const unsigned*)(g.a1 + kt * 32), (unsigned*)(sb + (wid + 4) * 1024), 16, 0, 0);
;   __builtin_amdgcn_global_load_lds((const unsigned*)(g.b0 + kt * 32), (unsigned*)(sb + 8192 + wid * 1024), 16, 0, 0);
;   __builtin_amdgcn_global_load_lds((const unsigned*)(g.b1 + kt * 32), (unsigned*)(sb + 8192 + (wid + 4) * 1024), 16, 0, 0);
; }
; __device__ __forceinline__ void gemm_prologue(const GemmOps& g, u16* lds) {
;   gemm_issue(g, 0, 0, (char*)lds); gemm_issue(g, 1, 1, (char*)lds);
; }
; __device__ void ph_gemm2(const P& p, u16* lds) {
;   const int lane = tid_() & 63, wid = tid_() >> 6, wm = wid >> 1, wn = wid & 1;
;   const int NT = 8, NTILES = 264 * NT;
;   int it = blockIdx.x;
;   if (it >= NTILES) return;
;   auto ops = [&](int t) __attribute__((always_inline)) { return gemm_ops(p_mix + (size_t)(t / NT) * 128 * DM, DM, p_WoutT + (size_t)(t % NT) * 128 * DM, DM); };
;   GemmOps g = ops(it);
;   __syncthreads();
;   gemm_prologue(g, lds);
.LBB0_597:
	s_cmp_lt_i32 s6, 6
	s_cselect_b64 s[0:1], -1, 0
	s_cmp_gt_i32 s7, 5
	s_cselect_b64 s[2:3], -1, 0
	s_and_b64 s[0:1], s[0:1], s[2:3]
	s_andn2_b64 vcc, exec, s[0:1]
	s_cbranch_vccnz .LBB0_691
	v_readlane_b32 s0, v228, 0
	v_mov_b32_e32 v0, v220
	v_mov_b32_e32 v1, v220
	s_cmpk_gt_i32 s0, 0x83f
	v_readlane_b32 s1, v228, 1
	s_cbranch_scc1 .LBB0_637
	v_readlane_b32 s0, v228, 2
	v_readlane_b32 s6, v228, 8
	v_readlane_b32 s7, v228, 9
	s_add_u32 s16, s6, 0x137c8000
	v_readlane_b32 s14, v228, 0
	s_addc_u32 s17, s7, 0
	s_and_b32 s81, s14, 7
	s_lshr_b32 s82, s14, 3
	s_lshr_b32 s83, s82, 6
	s_and_b32 s84, s82, 63
	s_cmp_lt_u32 s83, 4
	s_cselect_b32 s85, 3, 0
	s_cselect_b32 s86, 7, 0
	s_lshr_b32 s87, s84, s85
	s_and_b32 s84, s84, s86
	s_lshl_b32 s83, s83, 3
	s_add_u32 s83, s83, s84
	s_mul_i32 s81, s81, 33
	s_add_u32 s81, s81, s83
	s_mul_i32 s81, s81, 8
	s_add_u32 s80, s81, s87
	s_ashr_i32 s0, s80, 31
	v_readlane_b32 s2, v228, 4
	s_lshr_b32 s0, s0, 29
	s_add_i32 s2, s80, s0
	v_readlane_b32 s1, v228, 3
	s_ashr_i32 s0, s2, 3
	s_ashr_i32 s1, s0, 31
	s_lshl_b64 s[0:1], s[0:1], 18
	s_add_u32 s0, s16, s0
	s_addc_u32 s1, s17, s1
	s_add_u32 s18, s6, 0x5c0000
	s_addc_u32 s19, s7, 0
	s_and_b32 s2, s2, -8
	v_mov_b32_e32 v5, v220
	v_mov_b32_e32 v2, v220
	v_readlane_b32 s3, v228, 5
	s_sub_i32 s2, s80, s2
	s_ashr_i32 s3, s2, 31
	v_lshrrev_b32_e32 v3, 2, v5
	v_ashrrev_i32_e32 v2, 2, v2
	s_waitcnt vmcnt(0)
	v_lshrrev_b32_e32 v8, 4, v5
	s_lshl_b64 s[2:3], s[2:3], 18
	v_bfi_b32 v2, -16, v2, v3
	v_xor_b32_e32 v5, v8, v5
	s_add_u32 s2, s18, s2
	v_add_u32_e32 v4, 64, v2
	v_ashrrev_i32_e32 v3, 31, v2
	v_lshlrev_b32_e32 v5, 4, v5
	s_addc_u32 s3, s19, s3
	s_mov_b64 s[88:89], s[0:1]
	s_mov_b64 s[90:91], s[2:3]
	v_lshlrev_b64 v[2:3], 11, v[2:3]
	v_and_b32_e32 v68, 48, v5
	v_ashrrev_i32_e32 v5, 31, v4
	v_lshl_add_u64 v[6:7], s[0:1], 0, v[2:3]
	v_mov_b32_e32 v69, 0
	v_lshlrev_b64 v[4:5], 11, v[4:5]
	v_lshl_add_u64 v[2:3], s[2:3], 0, v[2:3]
	v_lshl_add_u64 v[74:75], v[2:3], 0, v[68:69]
	v_lshl_add_u64 v[2:3], s[2:3], 0, v[4:5]
	v_lshl_add_u64 v[76:77], v[2:3], 0, v[68:69]
	v_mov_b32_e32 v2, v220
	s_waitcnt lgkmcnt(0)
	s_barrier
	v_lshl_add_u64 v[70:71], v[6:7], 0, v[68:69]
	v_lshlrev_b32_e32 v2, 4, v2
	v_and_b32_e32 v2, 0xfffffc00, v2
	v_lshl_add_u64 v[6:7], s[0:1], 0, v[4:5]
	v_readfirstlane_b32 s0, v2
	v_add_u32_e32 v3, 0x1000, v2
	s_mov_b32 m0, s0
	v_readfirstlane_b32 s0, v3
	v_add_u32_e32 v3, 0x2000, v2
	v_lshl_add_u64 v[72:73], v[6:7], 0, v[68:69]
	s_mov_b32 m0, s0
	v_readfirstlane_b32 s0, v3
	v_add_u32_e32 v2, 0x3000, v2
	s_mov_b32 m0, s0
	v_readfirstlane_b32 s0, v2
	s_mov_b32 m0, s0
	v_mov_b32_e32 v4, v220
	v_lshl_add_u64 v[2:3], v[70:71], 0, 64
	v_lshlrev_b32_e32 v4, 4, v4
	v_and_b32_e32 v4, 0xfffffc00, v4
	v_add_u32_e32 v5, 0x4000, v4
	s_add_u32 s2, s6, 0x1ba11600
	v_readfirstlane_b32 s0, v5
	v_add_u32_e32 v5, 0x5000, v4
	s_mov_b32 m0, s0
	v_readfirstlane_b32 s0, v5
	v_add_u32_e32 v5, 0x6000, v4
	v_lshl_add_u64 v[2:3], v[72:73], 0, 64
	s_mov_b32 m0, s0
	v_readfirstlane_b32 s0, v5
	v_add_u32_e32 v4, 0x7000, v4
	v_lshl_add_u64 v[2:3], v[74:75], 0, 64
	s_mov_b32 m0, s0
	v_readfirstlane_b32 s0, v4
	v_lshl_add_u64 v[2:3], v[76:77], 0, 64
	s_mov_b32 m0, s0
	v_readlane_b32 s4, v228, 6
	s_addc_u32 s3, s7, 0
	v_readlane_b32 s5, v228, 7
	v_and_b32_e32 v86, 64, v1
	v_readlane_b32 s36, v228, 49
	s_add_u32 s4, s6, 0x3f40000
	v_lshlrev_b32_e32 v68, 2, v86
	v_readlane_b32 s37, v228, 50
	v_lshlrev_b32_e32 v0, 4, v0
	s_addc_u32 s5, s7, 0
	v_ashrrev_i32_e32 v1, 1, v1
	v_lshl_add_u64 v[2:3], s[36:37], 0, v[68:69]
	v_and_b32_e32 v68, 0xf0, v0
	s_add_u32 s6, s6, 0x1b9f0600
	v_and_b32_e32 v87, 0xffffffc0, v1
	v_lshl_add_u64 v[78:79], v[2:3], 0, v[68:69]
	s_addc_u32 s7, s7, 0
	s_mov_b32 s20, 0x3ffffc0
	s_movk_i32 s21, 0x13c0
	s_mov_b64 s[8:9], 0x80
	s_mov_b32 s22, 0x8000
	s_mov_b64 s[10:11], 0xc0
	s_mov_b64 s[12:13], 0x100
	s_movk_i32 s23, 0x1100
	s_movk_i32 s24, 0x440
	s_movk_i32 s25, 0x110
	s_mov_b32 s26, s14
	v_readlane_b32 s15, v228, 1
	v_readlane_b32 s38, v228, 51
	v_readlane_b32 s39, v228, 52
	v_readlane_b32 s40, v228, 53
	v_readlane_b32 s41, v228, 54
	v_readlane_b32 s42, v228, 55
	v_readlane_b32 s43, v228, 56
	v_readlane_b32 s44, v228, 57
	v_readlane_b32 s45, v228, 58
	v_readlane_b32 s46, v228, 59
	v_readlane_b32 s47, v228, 60
	v_readlane_b32 s48, v228, 61
	v_readlane_b32 s49, v228, 62
	v_readlane_b32 s50, v228, 63
	v_readlane_b32 s51, v227, 0
	v_lshrrev_b32_e32 v133, 3, v220
	v_lshlrev_b32_e32 v133, 11, v133
	v_bfe_u32 v134, v220, 4, 3
	v_and_b32_e32 v135, 7, v220
	v_xor_b32_e32 v134, v134, v135
	v_lshl_add_u32 v133, v134, 4, v133
	v_add_u32_e32 v134, 0x10000, v133
	v_add_u32_e32 v135, 0x20000, v133
	v_add_u32_e32 v136, 0x30000, v133
	v_and_b32_e32 v143, 15, v220
	v_bfe_u32 v144, v220, 4, 2
	v_bfe_u32 v145, v220, 1, 3
	v_xor_b32_e32 v144, v144, v145
	v_lshlrev_b32_e32 v144, 4, v144
	v_lshl_add_u32 v143, v143, 7, v144
	v_lshrrev_b32_e32 v144, 7, v220
	v_lshl_add_u32 v137, v144, 13, v143
	v_xor_b32_e32 v138, 64, v137
	v_bfe_u32 v144, v220, 6, 1
	v_lshl_add_u32 v139, v144, 13, v143
	v_add_u32_e32 v139, 0x4000, v139
	v_xor_b32_e32 v140, 64, v139
	v_lshl_add_u32 v141, v144, 10, v139
	v_lshl_add_u32 v142, v144, 10, v140
	v_readfirstlane_b32 s92, v220
	s_nop 0
	s_lshl_b32 s92, s92, 4
	s_add_u32 s93, s92, 0x8000
	s_mov_b32 m0, s92
	s_nop 0
	global_load_lds_dwordx4 v133, s[88:89]
	s_add_u32 m0, m0, 0x1000
	s_nop 0
	global_load_lds_dwordx4 v134, s[88:89]
	s_add_u32 m0, m0, 0x1000
	s_nop 0
	global_load_lds_dwordx4 v135, s[88:89]
	s_add_u32 m0, m0, 0x1000
	s_nop 0
	global_load_lds_dwordx4 v136, s[88:89]
	s_add_u32 m0, m0, 0x1000
	s_nop 0
	global_load_lds_dwordx4 v133, s[90:91]
	s_add_u32 m0, m0, 0x1000
	s_nop 0
	global_load_lds_dwordx4 v134, s[90:91]
	s_add_u32 m0, m0, 0x1000
	s_nop 0
	global_load_lds_dwordx4 v135, s[90:91]
	s_add_u32 m0, m0, 0x1000
	s_nop 0
	global_load_lds_dwordx4 v136, s[90:91]
	s_branch .LBB0_601

; __device__ __forceinline__ int tid_() { int t = threadIdx.x; asm volatile("" : "+v"(t)); return t; }
; __device__ __forceinline__ f32x4 mfma16(bf16x8 a, bf16x8 b, f32x4 c) { return __builtin_amdgcn_mfma_f32_16x16x32_bf16(a, b, c, 0, 0, 0); }
; #define RAW_BARRIER() do { asm volatile("s_waitcnt lgkmcnt(0)" ::: "memory"); __builtin_amdgcn_s_barrier(); } while (0)
; #define GEMM_STEP(J, BUF, NBUF) do { asm volatile("s_waitcnt vmcnt(4)" ::: "memory"); RAW_BARRIER(); \
;     if ((J) + 2 < nk) gemm_issue(g, (J) + 2, NBUF, L); comp(BUF); } while (0)
; __device__ __forceinline__ void gemm_main(f32x4 (&acc)[4][4], const GemmOps& g, int K, u16* lds) {
;   const int tid = tid_(), lane = tid & 63, wid = tid >> 6;
;   const int wm = wid >> 1, wn = wid & 1, fr = lane & 15, fq = lane >> 4;
;   char* L = (char*)lds;
;   int offA[4], offB[4];
; #pragma unroll
;   for (int i = 0; i < 4; ++i) {
;     const int Ra = wm * 64 + i * 16 + fr, Rb = wn * 64 + i * 16 + fr;
;     offA[i] = Ra * 64 + ((fq ^ ((Ra >> 2) & 3)) << 4);
;     offB[i] = 8192 + Rb * 64 + ((fq ^ ((Rb >> 2) & 3)) << 4);
;   }
;   auto comp = [&](int buf) __attribute__((always_inline)) {
;     const char* sb = L + buf * GEMM_STAGE_B;
;     bf16x8 a[4], b[4];
; #pragma unroll
;     for (int i = 0; i < 4; ++i) a[i] = *(const bf16x8*)(sb + offA[i]);
; #pragma unroll
;     for (int j = 0; j < 4; ++j) b[j] = *(const bf16x8*)(sb + offB[j]);
; #pragma unroll
;     for (int i = 0; i < 4; ++i)
; #pragma unroll
;       for (int j = 0; j < 4; ++j) acc[i][j] = mfma16(a[i], b[j], acc[i][j]);
;   };
;   const int nk = K >> 5;
;     ...
;   int j = 0;
;   for (; j + 3 <= nk - 1; j += 3) {
;     GEMM_STEP(j, 0, 2);
;     GEMM_STEP(j + 1, 1, 0);
;     GEMM_STEP(j + 2, 2, 1);
;   }
;   GEMM_STEP(j, 0, 2);
;   asm volatile("s_waitcnt vmcnt(0)" ::: "memory");
;   RAW_BARRIER();
;   comp(1);
;     ...
; }
; __device__ __forceinline__ void zero_acc(f32x4 (&acc)[4][4]) {
; #pragma unroll
;   for (int i = 0; i < 4; ++i)
; #pragma unroll
;     for (int j = 0; j < 4; ++j) acc[i][j] = f32x4{0.f, 0.f, 0.f, 0.f};
; }
.LBB0_602:
	v_mov_b32_e32 v52, 0
	v_mov_b32_e32 v53, 0
	v_mov_b32_e32 v54, 0
	v_mov_b32_e32 v55, 0
	v_mov_b32_e32 v60, 0
	v_mov_b32_e32 v61, 0
	v_mov_b32_e32 v62, 0
	v_mov_b32_e32 v63, 0
	v_mov_b32_e32 v56, 0
	v_mov_b32_e32 v57, 0
	v_mov_b32_e32 v58, 0
	v_mov_b32_e32 v59, 0
	v_mov_b32_e32 v64, 0
	v_mov_b32_e32 v65, 0
	v_mov_b32_e32 v66, 0
	v_mov_b32_e32 v67, 0
	v_mov_b32_e32 v44, 0
	v_mov_b32_e32 v45, 0
	v_mov_b32_e32 v46, 0
	v_mov_b32_e32 v47, 0
	v_mov_b32_e32 v48, 0
	v_mov_b32_e32 v49, 0
	v_mov_b32_e32 v50, 0
	v_mov_b32_e32 v51, 0
	v_mov_b32_e32 v36, 0
	v_mov_b32_e32 v37, 0
	v_mov_b32_e32 v38, 0
	v_mov_b32_e32 v39, 0
	v_mov_b32_e32 v40, 0
	v_mov_b32_e32 v41, 0
	v_mov_b32_e32 v42, 0
	v_mov_b32_e32 v43, 0
	v_mov_b32_e32 v28, 0
	v_mov_b32_e32 v29, 0
	v_mov_b32_e32 v30, 0
	v_mov_b32_e32 v31, 0
	v_mov_b32_e32 v32, 0
	v_mov_b32_e32 v33, 0
	v_mov_b32_e32 v34, 0
	v_mov_b32_e32 v35, 0
	v_mov_b32_e32 v20, 0
	v_mov_b32_e32 v21, 0
	v_mov_b32_e32 v22, 0
	v_mov_b32_e32 v23, 0
	v_mov_b32_e32 v24, 0
	v_mov_b32_e32 v25, 0
	v_mov_b32_e32 v26, 0
	v_mov_b32_e32 v27, 0
	v_mov_b32_e32 v4, 0
	v_mov_b32_e32 v5, 0
	v_mov_b32_e32 v6, 0
	v_mov_b32_e32 v7, 0
	v_mov_b32_e32 v8, 0
	v_mov_b32_e32 v9, 0
	v_mov_b32_e32 v10, 0
	v_mov_b32_e32 v11, 0
	v_mov_b32_e32 v12, 0
	v_mov_b32_e32 v13, 0
	v_mov_b32_e32 v14, 0
	v_mov_b32_e32 v15, 0
	v_mov_b32_e32 v16, 0
	v_mov_b32_e32 v17, 0
	v_mov_b32_e32 v18, 0
	v_mov_b32_e32 v19, 0
	s_mov_b32 s94, 7
.Lg2_k:
	s_waitcnt vmcnt(0)
	s_barrier
	s_add_u32 s88, s88, 0x80
	s_addc_u32 s89, s89, 0
	s_add_u32 s90, s90, 0x80
	s_addc_u32 s91, s91, 0
	s_mov_b32 m0, s93
	ds_read_b128 v[148:151], v137 offset:0
	global_load_lds_dwordx4 v133, s[88:89]
	s_add_u32 m0, m0, 0x1000
	ds_read_b128 v[152:155], v137 offset:2048
	global_load_lds_dwordx4 v134, s[88:89]
	s_add_u32 m0, m0, 0x1000
	ds_read_b128 v[156:159], v137 offset:4096
	global_load_lds_dwordx4 v135, s[88:89]
	s_add_u32 m0, m0, 0x1000
	ds_read_b128 v[160:163], v137 offset:6144
	global_load_lds_dwordx4 v136, s[88:89]
	s_add_u32 m0, m0, 0x1000
	ds_read_b128 v[180:183], v139 offset:0
	global_load_lds_dwordx4 v133, s[90:91]
	s_add_u32 m0, m0, 0x1000
	ds_read_b128 v[184:187], v139 offset:2048
	global_load_lds_dwordx4 v134, s[90:91]
	s_add_u32 m0, m0, 0x1400
	ds_read_b128 v[188:191], v139 offset:4096
	global_load_lds_dwordx4 v135, s[90:91]
	s_add_u32 m0, m0, 0x1000
	ds_read_b128 v[192:195], v139 offset:6144
	global_load_lds_dwordx4 v136, s[90:91]
	ds_read_b128 v[164:167], v138 offset:0
	ds_read_b128 v[168:171], v138 offset:2048
	ds_read_b128 v[172:175], v138 offset:4096
	ds_read_b128 v[176:179], v138 offset:6144
	ds_read_b128 v[196:199], v140 offset:0
	ds_read_b128 v[200:203], v140 offset:2048
	ds_read_b128 v[204:207], v140 offset:4096
	ds_read_b128 v[208:211], v140 offset:6144
	s_waitcnt lgkmcnt(8)
	v_mfma_f32_16x16x32_bf16 v[52:55], v[148:151], v[180:183], v[52:55]
	v_mfma_f32_16x16x32_bf16 v[60:63], v[148:151], v[184:187], v[60:63]
	v_mfma_f32_16x16x32_bf16 v[56:59], v[148:151], v[188:191], v[56:59]
	v_mfma_f32_16x16x32_bf16 v[64:67], v[148:151], v[192:195], v[64:67]
	v_mfma_f32_16x16x32_bf16 v[44:47], v[152:155], v[180:183], v[44:47]
	v_mfma_f32_16x16x32_bf16 v[48:51], v[152:155], v[184:187], v[48:51]
	v_mfma_f32_16x16x32_bf16 v[36:39], v[152:155], v[188:191], v[36:39]
	v_mfma_f32_16x16x32_bf16 v[40:43], v[152:155], v[192:195], v[40:43]
	v_mfma_f32_16x16x32_bf16 v[28:31], v[156:159], v[180:183], v[28:31]
	v_mfma_f32_16x16x32_bf16 v[32:35], v[156:159], v[184:187], v[32:35]
	v_mfma_f32_16x16x32_bf16 v[20:23], v[156:159], v[188:191], v[20:23]
	v_mfma_f32_16x16x32_bf16 v[24:27], v[156:159], v[192:195], v[24:27]
	v_mfma_f32_16x16x32_bf16 v[4:7], v[160:163], v[180:183], v[4:7]
	v_mfma_f32_16x16x32_bf16 v[8:11], v[160:163], v[184:187], v[8:11]
	v_mfma_f32_16x16x32_bf16 v[12:15], v[160:163], v[188:191], v[12:15]
	v_mfma_f32_16x16x32_bf16 v[16:19], v[160:163], v[192:195], v[16:19]
	s_waitcnt lgkmcnt(0)
	v_mfma_f32_16x16x32_bf16 v[52:55], v[164:167], v[196:199], v[52:55]
	v_mfma_f32_16x16x32_bf16 v[60:63], v[164:167], v[200:203], v[60:63]
	v_mfma_f32_16x16x32_bf16 v[56:59], v[164:167], v[204:207], v[56:59]
	v_mfma_f32_16x16x32_bf16 v[64:67], v[164:167], v[208:211], v[64:67]
	v_mfma_f32_16x16x32_bf16 v[44:47], v[168:171], v[196:199], v[44:47]
	v_mfma_f32_16x16x32_bf16 v[48:51], v[168:171], v[200:203], v[48:51]
	v_mfma_f32_16x16x32_bf16 v[36:39], v[168:171], v[204:207], v[36:39]
	v_mfma_f32_16x16x32_bf16 v[40:43], v[168:171], v[208:211], v[40:43]
	v_mfma_f32_16x16x32_bf16 v[28:31], v[172:175], v[196:199], v[28:31]
	v_mfma_f32_16x16x32_bf16 v[32:35], v[172:175], v[200:203], v[32:35]
	v_mfma_f32_16x16x32_bf16 v[20:23], v[172:175], v[204:207], v[20:23]
	v_mfma_f32_16x16x32_bf16 v[24:27], v[172:175], v[208:211], v[24:27]
	v_mfma_f32_16x16x32_bf16 v[4:7], v[176:179], v[196:199], v[4:7]
	v_mfma_f32_16x16x32_bf16 v[8:11], v[176:179], v[200:203], v[8:11]
	v_mfma_f32_16x16x32_bf16 v[12:15], v[176:179], v[204:207], v[12:15]
	v_mfma_f32_16x16x32_bf16 v[16:19], v[176:179], v[208:211], v[16:19]
	s_waitcnt vmcnt(0)
	s_barrier
; __device__ __forceinline__ int tid_() { int t = threadIdx.x; asm volatile("" : "+v"(t)); return t; }
; __device__ __forceinline__ f32x4 mfma16(bf16x8 a, bf16x8 b, f32x4 c) { return __builtin_amdgcn_mfma_f32_16x16x32_bf16(a, b, c, 0, 0, 0); }
; #define RAW_BARRIER() do { asm volatile("s_waitcnt lgkmcnt(0)" ::: "memory"); __builtin_amdgcn_s_barrier(); } while (0)
; #define GEMM_STEP(J, BUF, NBUF) do { asm volatile("s_waitcnt vmcnt(4)" ::: "memory"); RAW_BARRIER(); \
;     if ((J) + 2 < nk) gemm_issue(g, (J) + 2, NBUF, L); comp(BUF); } while (0)
; __device__ __forceinline__ void gemm_main(f32x4 (&acc)[4][4], const GemmOps& g, int K, u16* lds) {
;   const int tid = tid_(), lane = tid & 63, wid = tid >> 6;
;   const int wm = wid >> 1, wn = wid & 1, fr = lane & 15, fq = lane >> 4;
;   char* L = (char*)lds;
;   int offA[4], offB[4];
; #pragma unroll
;   for (int i = 0; i < 4; ++i) {
;     const int Ra = wm * 64 + i * 16 + fr, Rb = wn * 64 + i * 16 + fr;
;     offA[i] = Ra * 64 + ((fq ^ ((Ra >> 2) & 3)) << 4);
;     offB[i] = 8192 + Rb * 64 + ((fq ^ ((Rb >> 2) & 3)) << 4);
;   }
;   auto comp = [&](int buf) __attribute__((always_inline)) {
;     const char* sb = L + buf * GEMM_STAGE_B;
;     bf16x8 a[4], b[4];
; #pragma unroll
;     for (int i = 0; i < 4; ++i) a[i] = *(const bf16x8*)(sb + offA[i]);
; #pragma unroll
;     for (int j = 0; j < 4; ++j) b[j] = *(const bf16x8*)(sb + offB[j]);
; #pragma unroll
;     for (int i = 0; i < 4; ++i)
; #pragma unroll
;       for (int j = 0; j < 4; ++j) acc[i][j] = mfma16(a[i], b[j], acc[i][j]);
;   };
;   const int nk = K >> 5;
;     ...
;   int j = 0;
;   for (; j + 3 <= nk - 1; j += 3) {
;     GEMM_STEP(j, 0, 2);
;     GEMM_STEP(j + 1, 1, 0);
;     GEMM_STEP(j + 2, 2, 1);
;   }
;   GEMM_STEP(j, 0, 2);
;   asm volatile("s_waitcnt vmcnt(0)" ::: "memory");
;   RAW_BARRIER();
;   comp(1);
	s_add_u32 s88, s88, 0x80
	s_addc_u32 s89, s89, 0
	s_add_u32 s90, s90, 0x80
	s_addc_u32 s91, s91, 0
	s_mov_b32 m0, s92
	ds_read_b128 v[148:151], v137 offset:32768
	global_load_lds_dwordx4 v133, s[88:89]
	s_add_u32 m0, m0, 0x1000
	ds_read_b128 v[152:155], v137 offset:34816
	global_load_lds_dwordx4 v134, s[88:89]
	s_add_u32 m0, m0, 0x1000
	ds_read_b128 v[156:159], v137 offset:36864
	global_load_lds_dwordx4 v135, s[88:89]
	s_add_u32 m0, m0, 0x1000
	ds_read_b128 v[160:163], v137 offset:38912
	global_load_lds_dwordx4 v136, s[88:89]
	s_add_u32 m0, m0, 0x1000
	ds_read_b128 v[180:183], v141 offset:32768
	global_load_lds_dwordx4 v133, s[90:91]
	s_add_u32 m0, m0, 0x1000
	ds_read_b128 v[184:187], v141 offset:34816
	global_load_lds_dwordx4 v134, s[90:91]
	s_add_u32 m0, m0, 0x1000
	ds_read_b128 v[188:191], v141 offset:36864
	global_load_lds_dwordx4 v135, s[90:91]
	s_add_u32 m0, m0, 0x1000
	ds_read_b128 v[192:195], v141 offset:38912
	global_load_lds_dwordx4 v136, s[90:91]
	ds_read_b128 v[164:167], v138 offset:32768
	ds_read_b128 v[168:171], v138 offset:34816
	ds_read_b128 v[172:175], v138 offset:36864
	ds_read_b128 v[176:179], v138 offset:38912
	ds_read_b128 v[196:199], v142 offset:32768
	ds_read_b128 v[200:203], v142 offset:34816
	ds_read_b128 v[204:207], v142 offset:36864
	ds_read_b128 v[208:211], v142 offset:38912
	s_waitcnt lgkmcnt(8)
	v_mfma_f32_16x16x32_bf16 v[52:55], v[148:151], v[180:183], v[52:55]
	v_mfma_f32_16x16x32_bf16 v[60:63], v[148:151], v[184:187], v[60:63]
	v_mfma_f32_16x16x32_bf16 v[56:59], v[148:151], v[188:191], v[56:59]
	v_mfma_f32_16x16x32_bf16 v[64:67], v[148:151], v[192:195], v[64:67]
	v_mfma_f32_16x16x32_bf16 v[44:47], v[152:155], v[180:183], v[44:47]
	v_mfma_f32_16x16x32_bf16 v[48:51], v[152:155], v[184:187], v[48:51]
	v_mfma_f32_16x16x32_bf16 v[36:39], v[152:155], v[188:191], v[36:39]
	v_mfma_f32_16x16x32_bf16 v[40:43], v[152:155], v[192:195], v[40:43]
	v_mfma_f32_16x16x32_bf16 v[28:31], v[156:159], v[180:183], v[28:31]
	v_mfma_f32_16x16x32_bf16 v[32:35], v[156:159], v[184:187], v[32:35]
	v_mfma_f32_16x16x32_bf16 v[20:23], v[156:159], v[188:191], v[20:23]
	v_mfma_f32_16x16x32_bf16 v[24:27], v[156:159], v[192:195], v[24:27]
	v_mfma_f32_16x16x32_bf16 v[4:7], v[160:163], v[180:183], v[4:7]
	v_mfma_f32_16x16x32_bf16 v[8:11], v[160:163], v[184:187], v[8:11]
	v_mfma_f32_16x16x32_bf16 v[12:15], v[160:163], v[188:191], v[12:15]
	v_mfma_f32_16x16x32_bf16 v[16:19], v[160:163], v[192:195], v[16:19]
	s_waitcnt lgkmcnt(0)
	v_mfma_f32_16x16x32_bf16 v[52:55], v[164:167], v[196:199], v[52:55]
	v_mfma_f32_16x16x32_bf16 v[60:63], v[164:167], v[200:203], v[60:63]
	v_mfma_f32_16x16x32_bf16 v[56:59], v[164:167], v[204:207], v[56:59]
	v_mfma_f32_16x16x32_bf16 v[64:67], v[164:167], v[208:211], v[64:67]
	v_mfma_f32_16x16x32_bf16 v[44:47], v[168:171], v[196:199], v[44:47]
	v_mfma_f32_16x16x32_bf16 v[48:51], v[168:171], v[200:203], v[48:51]
	v_mfma_f32_16x16x32_bf16 v[36:39], v[168:171], v[204:207], v[36:39]
	v_mfma_f32_16x16x32_bf16 v[40:43], v[168:171], v[208:211], v[40:43]
	v_mfma_f32_16x16x32_bf16 v[28:31], v[172:175], v[196:199], v[28:31]
	v_mfma_f32_16x16x32_bf16 v[32:35], v[172:175], v[200:203], v[32:35]
	v_mfma_f32_16x16x32_bf16 v[20:23], v[172:175], v[204:207], v[20:23]
	v_mfma_f32_16x16x32_bf16 v[24:27], v[172:175], v[208:211], v[24:27]
	v_mfma_f32_16x16x32_bf16 v[4:7], v[176:179], v[196:199], v[4:7]
	v_mfma_f32_16x16x32_bf16 v[8:11], v[176:179], v[200:203], v[8:11]
	v_mfma_f32_16x16x32_bf16 v[12:15], v[176:179], v[204:207], v[12:15]
	v_mfma_f32_16x16x32_bf16 v[16:19], v[176:179], v[208:211], v[16:19]
	s_sub_u32 s94, s94, 1
	s_cmp_lg_u32 s94, 0
	s_cbranch_scc1 .Lg2_k
	s_waitcnt vmcnt(0)
	s_barrier
	s_add_u32 s88, s88, 0x80
	s_addc_u32 s89, s89, 0
	s_add_u32 s90, s90, 0x80
	s_addc_u32 s91, s91, 0
	s_mov_b32 m0, s93
	ds_read_b128 v[148:151], v137 offset:0
	global_load_lds_dwordx4 v133, s[88:89]
	s_add_u32 m0, m0, 0x1000
	ds_read_b128 v[152:155], v137 offset:2048
	global_load_lds_dwordx4 v134, s[88:89]
	s_add_u32 m0, m0, 0x1000
	ds_read_b128 v[156:159], v137 offset:4096
	global_load_lds_dwordx4 v135, s[88:89]
	s_add_u32 m0, m0, 0x1000
	ds_read_b128 v[160:163], v137 offset:6144
	global_load_lds_dwordx4 v136, s[88:89]
	s_add_u32 m0, m0, 0x1000
	ds_read_b128 v[180:183], v139 offset:0
	global_load_lds_dwordx4 v133, s[90:91]
	s_add_u32 m0, m0, 0x1000
	ds_read_b128 v[184:187], v139 offset:2048
	global_load_lds_dwordx4 v134, s[90:91]
	s_add_u32 m0, m0, 0x1400
	ds_read_b128 v[188:191], v139 offset:4096
	global_load_lds_dwordx4 v135, s[90:91]
	s_add_u32 m0, m0, 0x1000
	ds_read_b128 v[192:195], v139 offset:6144
	global_load_lds_dwordx4 v136, s[90:91]
	ds_read_b128 v[164:167], v138 offset:0
	ds_read_b128 v[168:171], v138 offset:2048
	ds_read_b128 v[172:175], v138 offset:4096
	ds_read_b128 v[176:179], v138 offset:6144
	ds_read_b128 v[196:199], v140 offset:0
	ds_read_b128 v[200:203], v140 offset:2048
	ds_read_b128 v[204:207], v140 offset:4096
	ds_read_b128 v[208:211], v140 offset:6144
	s_waitcnt lgkmcnt(8)
	v_mfma_f32_16x16x32_bf16 v[52:55], v[148:151], v[180:183], v[52:55]
	v_mfma_f32_16x16x32_bf16 v[60:63], v[148:151], v[184:187], v[60:63]
	v_mfma_f32_16x16x32_bf16 v[56:59], v[148:151], v[188:191], v[56:59]
	v_mfma_f32_16x16x32_bf16 v[64:67], v[148:151], v[192:195], v[64:67]
	v_mfma_f32_16x16x32_bf16 v[44:47], v[152:155], v[180:183], v[44:47]
	v_mfma_f32_16x16x32_bf16 v[48:51], v[152:155], v[184:187], v[48:51]
	v_mfma_f32_16x16x32_bf16 v[36:39], v[152:155], v[188:191], v[36:39]
	v_mfma_f32_16x16x32_bf16 v[40:43], v[152:155], v[192:195], v[40:43]
	v_mfma_f32_16x16x32_bf16 v[28:31], v[156:159], v[180:183], v[28:31]
	v_mfma_f32_16x16x32_bf16 v[32:35], v[156:159], v[184:187], v[32:35]
	v_mfma_f32_16x16x32_bf16 v[20:23], v[156:159], v[188:191], v[20:23]
	v_mfma_f32_16x16x32_bf16 v[24:27], v[156:159], v[192:195], v[24:27]
	v_mfma_f32_16x16x32_bf16 v[4:7], v[160:163], v[180:183], v[4:7]
	v_mfma_f32_16x16x32_bf16 v[8:11], v[160:163], v[184:187], v[8:11]
	v_mfma_f32_16x16x32_bf16 v[12:15], v[160:163], v[188:191], v[12:15]
	v_mfma_f32_16x16x32_bf16 v[16:19], v[160:163], v[192:195], v[16:19]
	s_waitcnt lgkmcnt(0)
; __device__ __forceinline__ f32x4 mfma16(bf16x8 a, bf16x8 b, f32x4 c) { return __builtin_amdgcn_mfma_f32_16x16x32_bf16(a, b, c, 0, 0, 0); }
; #define RAW_BARRIER() do { asm volatile("s_waitcnt lgkmcnt(0)" ::: "memory"); __builtin_amdgcn_s_barrier(); } while (0)
; #define GEMM_STEP(J, BUF, NBUF) do { asm volatile("s_waitcnt vmcnt(4)" ::: "memory"); RAW_BARRIER(); \
;     if ((J) + 2 < nk) gemm_issue(g, (J) + 2, NBUF, L); comp(BUF); } while (0)
; __device__ __forceinline__ void gemm_main(f32x4 (&acc)[4][4], const GemmOps& g, int K, u16* lds) {
;     ...
;   auto comp = [&](int buf) __attribute__((always_inline)) {
;     const char* sb = L + buf * GEMM_STAGE_B;
;     bf16x8 a[4], b[4];
; #pragma unroll
;     for (int i = 0; i < 4; ++i) a[i] = *(const bf16x8*)(sb + offA[i]);
; #pragma unroll
;     for (int j = 0; j < 4; ++j) b[j] = *(const bf16x8*)(sb + offB[j]);
; #pragma unroll
;     for (int i = 0; i < 4; ++i)
; #pragma unroll
;       for (int j = 0; j < 4; ++j) acc[i][j] = mfma16(a[i], b[j], acc[i][j]);
;   };
;   const int nk = K >> 5;
;     ...
;   int j = 0;
;   for (; j + 3 <= nk - 1; j += 3) {
;     GEMM_STEP(j, 0, 2);
;     GEMM_STEP(j + 1, 1, 0);
;     GEMM_STEP(j + 2, 2, 1);
;   }
;   GEMM_STEP(j, 0, 2);
;   asm volatile("s_waitcnt vmcnt(0)" ::: "memory");
;   RAW_BARRIER();
;   comp(1);
	v_mfma_f32_16x16x32_bf16 v[52:55], v[164:167], v[196:199], v[52:55]
	v_mfma_f32_16x16x32_bf16 v[60:63], v[164:167], v[200:203], v[60:63]
	v_mfma_f32_16x16x32_bf16 v[56:59], v[164:167], v[204:207], v[56:59]
	v_mfma_f32_16x16x32_bf16 v[64:67], v[164:167], v[208:211], v[64:67]
	v_mfma_f32_16x16x32_bf16 v[44:47], v[168:171], v[196:199], v[44:47]
	v_mfma_f32_16x16x32_bf16 v[48:51], v[168:171], v[200:203], v[48:51]
	v_mfma_f32_16x16x32_bf16 v[36:39], v[168:171], v[204:207], v[36:39]
	v_mfma_f32_16x16x32_bf16 v[40:43], v[168:171], v[208:211], v[40:43]
	v_mfma_f32_16x16x32_bf16 v[28:31], v[172:175], v[196:199], v[28:31]
	v_mfma_f32_16x16x32_bf16 v[32:35], v[172:175], v[200:203], v[32:35]
	v_mfma_f32_16x16x32_bf16 v[20:23], v[172:175], v[204:207], v[20:23]
	v_mfma_f32_16x16x32_bf16 v[24:27], v[172:175], v[208:211], v[24:27]
	v_mfma_f32_16x16x32_bf16 v[4:7], v[176:179], v[196:199], v[4:7]
	v_mfma_f32_16x16x32_bf16 v[8:11], v[176:179], v[200:203], v[8:11]
	v_mfma_f32_16x16x32_bf16 v[12:15], v[176:179], v[204:207], v[12:15]
	v_mfma_f32_16x16x32_bf16 v[16:19], v[176:179], v[208:211], v[16:19]
	s_waitcnt vmcnt(0)
	s_barrier
	ds_read_b128 v[148:151], v137 offset:32768
	ds_read_b128 v[152:155], v137 offset:34816
	ds_read_b128 v[156:159], v137 offset:36864
	ds_read_b128 v[160:163], v137 offset:38912
	ds_read_b128 v[180:183], v141 offset:32768
	ds_read_b128 v[184:187], v141 offset:34816
	ds_read_b128 v[188:191], v141 offset:36864
	ds_read_b128 v[192:195], v141 offset:38912
	ds_read_b128 v[164:167], v138 offset:32768
	ds_read_b128 v[168:171], v138 offset:34816
	ds_read_b128 v[172:175], v138 offset:36864
	ds_read_b128 v[176:179], v138 offset:38912
	ds_read_b128 v[196:199], v142 offset:32768
	ds_read_b128 v[200:203], v142 offset:34816
	ds_read_b128 v[204:207], v142 offset:36864
	ds_read_b128 v[208:211], v142 offset:38912
	s_waitcnt lgkmcnt(8)
	v_mfma_f32_16x16x32_bf16 v[52:55], v[148:151], v[180:183], v[52:55]
	v_mfma_f32_16x16x32_bf16 v[60:63], v[148:151], v[184:187], v[60:63]
	v_mfma_f32_16x16x32_bf16 v[56:59], v[148:151], v[188:191], v[56:59]
	v_mfma_f32_16x16x32_bf16 v[64:67], v[148:151], v[192:195], v[64:67]
	v_mfma_f32_16x16x32_bf16 v[44:47], v[152:155], v[180:183], v[44:47]
	v_mfma_f32_16x16x32_bf16 v[48:51], v[152:155], v[184:187], v[48:51]
	v_mfma_f32_16x16x32_bf16 v[36:39], v[152:155], v[188:191], v[36:39]
	v_mfma_f32_16x16x32_bf16 v[40:43], v[152:155], v[192:195], v[40:43]
	v_mfma_f32_16x16x32_bf16 v[28:31], v[156:159], v[180:183], v[28:31]
	v_mfma_f32_16x16x32_bf16 v[32:35], v[156:159], v[184:187], v[32:35]
	v_mfma_f32_16x16x32_bf16 v[20:23], v[156:159], v[188:191], v[20:23]
	v_mfma_f32_16x16x32_bf16 v[24:27], v[156:159], v[192:195], v[24:27]
	v_mfma_f32_16x16x32_bf16 v[4:7], v[160:163], v[180:183], v[4:7]
	v_mfma_f32_16x16x32_bf16 v[8:11], v[160:163], v[184:187], v[8:11]
	v_mfma_f32_16x16x32_bf16 v[12:15], v[160:163], v[188:191], v[12:15]
	v_mfma_f32_16x16x32_bf16 v[16:19], v[160:163], v[192:195], v[16:19]
	s_waitcnt lgkmcnt(0)
	v_mfma_f32_16x16x32_bf16 v[52:55], v[164:167], v[196:199], v[52:55]
	v_mfma_f32_16x16x32_bf16 v[60:63], v[164:167], v[200:203], v[60:63]
	v_mfma_f32_16x16x32_bf16 v[56:59], v[164:167], v[204:207], v[56:59]
	v_mfma_f32_16x16x32_bf16 v[64:67], v[164:167], v[208:211], v[64:67]
	v_mfma_f32_16x16x32_bf16 v[44:47], v[168:171], v[196:199], v[44:47]
	v_mfma_f32_16x16x32_bf16 v[48:51], v[168:171], v[200:203], v[48:51]
	v_mfma_f32_16x16x32_bf16 v[36:39], v[168:171], v[204:207], v[36:39]
	v_mfma_f32_16x16x32_bf16 v[40:43], v[168:171], v[208:211], v[40:43]
	v_mfma_f32_16x16x32_bf16 v[28:31], v[172:175], v[196:199], v[28:31]
	v_mfma_f32_16x16x32_bf16 v[32:35], v[172:175], v[200:203], v[32:35]
	v_mfma_f32_16x16x32_bf16 v[20:23], v[172:175], v[204:207], v[20:23]
	v_mfma_f32_16x16x32_bf16 v[24:27], v[172:175], v[208:211], v[24:27]
	v_mfma_f32_16x16x32_bf16 v[4:7], v[176:179], v[196:199], v[4:7]
	v_mfma_f32_16x16x32_bf16 v[8:11], v[176:179], v[200:203], v[8:11]
	v_mfma_f32_16x16x32_bf16 v[12:15], v[176:179], v[204:207], v[12:15]
	v_mfma_f32_16x16x32_bf16 v[16:19], v[176:179], v[208:211], v[16:19]
	s_waitcnt lgkmcnt(0)
	s_barrier
; __device__ __forceinline__ int tid_() { int t = threadIdx.x; asm volatile("" : "+v"(t)); return t; }
; __device__ __forceinline__ GemmOps gemm_ops(const u16* A, int lda, const u16* B, int ldb) {
;   const int lane = tid_() & 63, wid = tid_() >> 6, rr = lane >> 2, c = lane & 3;
;   const int R0 = wid * 16 + rr, R1 = (wid + 4) * 16 + rr;
;   GemmOps g;
;   g.a0 = A + (size_t)R0 * lda + ((c ^ ((R0 >> 2) & 3)) << 3);
;   g.a1 = A + (size_t)R1 * lda + ((c ^ ((R1 >> 2) & 3)) << 3);
;   g.b0 = B + (size_t)R0 * ldb + ((c ^ ((R0 >> 2) & 3)) << 3);
;   g.b1 = B + (size_t)R1 * ldb + ((c ^ ((R1 >> 2) & 3)) << 3);
;   return g;
; }
; __device__ __forceinline__ void gemm_issue(const GemmOps& g, int kt, int buf, char* L) {
;   const int wid = tid_() >> 6;
;   char* sb = L + buf * GEMM_STAGE_B;
;   __builtin_amdgcn_global_load_lds((const unsigned*)(g.a0 + kt * 32), (unsigned*)(sb + wid * 1024), 16, 0, 0);
;   __builtin_amdgcn_global_load_lds((const unsigned*)(g.a1 + kt * 32), (unsigned*)(sb + (wid + 4) * 1024), 16, 0, 0);
;   __builtin_amdgcn_global_load_lds((const unsigned*)(g.b0 + kt * 32), (unsigned*)(sb + 8192 + wid * 1024), 16, 0, 0);
;   __builtin_amdgcn_global_load_lds((const unsigned*)(g.b1 + kt * 32), (unsigned*)(sb + 8192 + (wid + 4) * 1024), 16, 0, 0);
; }
; __device__ __forceinline__ void gemm_prologue(const GemmOps& g, u16* lds) {
;   gemm_issue(g, 0, 0, (char*)lds); gemm_issue(g, 1, 1, (char*)lds);
; }
; __device__ void ph_gemm2(const P& p, u16* lds) {
;     ...
;     const int itn = it + gridDim.x; const bool more = itn < NTILES;
;     __syncthreads();
;     if (more) { g = ops(itn); gemm_prologue(g, lds); }
	s_nop 7
	v_readlane_b32 s0, v228, 10
	s_add_i32 s26, s27, s0
	s_cmpk_gt_i32 s26, 0x83f
	s_cselect_b64 s[14:15], -1, 0
	s_and_b64 vcc, exec, s[14:15]
	v_readlane_b32 s1, v228, 11
	s_cbranch_vccnz .LBB0_605
	s_and_b32 s81, s26, 7
	s_lshr_b32 s82, s26, 3
	s_lshr_b32 s83, s82, 6
	s_and_b32 s84, s82, 63
	s_cmp_lt_u32 s83, 4
	s_cselect_b32 s85, 3, 0
	s_cselect_b32 s86, 7, 0
	s_lshr_b32 s87, s84, s85
	s_and_b32 s84, s84, s86
	s_lshl_b32 s83, s83, 3
	s_add_u32 s83, s83, s84
	s_mul_i32 s81, s81, 33
	s_add_u32 s81, s81, s83
	s_mul_i32 s81, s81, 8
	s_add_u32 s80, s81, s87
	s_ashr_i32 s0, s80, 31
	s_lshr_b32 s0, s0, 29
	s_add_i32 s28, s80, s0
	s_ashr_i32 s0, s28, 3
	s_ashr_i32 s1, s0, 31
	s_lshl_b64 s[0:1], s[0:1], 18
	s_add_u32 s0, s16, s0
	s_addc_u32 s1, s17, s1
	s_and_b32 s28, s28, -8
	v_mov_b32_e32 v3, v220
	v_mov_b32_e32 v0, v220
	s_sub_i32 s28, s80, s28
	s_ashr_i32 s29, s28, 31
	v_lshrrev_b32_e32 v1, 2, v3
	v_ashrrev_i32_e32 v0, 2, v0
	v_lshrrev_b32_e32 v68, 4, v3
	s_lshl_b64 s[28:29], s[28:29], 18
	v_bfi_b32 v0, -16, v0, v1
	v_xor_b32_e32 v3, v68, v3
	s_add_u32 s28, s18, s28
	v_add_u32_e32 v2, 64, v0
	v_ashrrev_i32_e32 v1, 31, v0
	v_lshlrev_b32_e32 v3, 4, v3
	s_addc_u32 s29, s19, s29
	s_mov_b64 s[88:89], s[0:1]
	s_mov_b64 s[90:91], s[28:29]
	v_lshlrev_b64 v[0:1], 11, v[0:1]
	v_and_b32_e32 v68, 48, v3
	v_ashrrev_i32_e32 v3, 31, v2
	v_lshl_add_u64 v[70:71], s[0:1], 0, v[0:1]
	v_lshlrev_b64 v[2:3], 11, v[2:3]
	v_lshl_add_u64 v[0:1], s[28:29], 0, v[0:1]
	v_lshl_add_u64 v[74:75], v[0:1], 0, v[68:69]
	v_lshl_add_u64 v[0:1], s[28:29], 0, v[2:3]
	v_lshl_add_u64 v[76:77], v[0:1], 0, v[68:69]
	v_mov_b32_e32 v0, v220
	v_lshl_add_u64 v[72:73], s[0:1], 0, v[2:3]
	v_lshlrev_b32_e32 v0, 4, v0
	v_and_b32_e32 v0, 0xfffffc00, v0
	v_add_u32_e32 v1, 0x1000, v0
	v_readfirstlane_b32 s0, v0
	v_lshl_add_u64 v[70:71], v[70:71], 0, v[68:69]
	s_mov_b32 m0, s0
	v_readfirstlane_b32 s0, v1
	v_add_u32_e32 v1, 0x2000, v0
	v_lshl_add_u64 v[72:73], v[72:73], 0, v[68:69]
	s_mov_b32 m0, s0
	v_readfirstlane_b32 s0, v1
	v_add_u32_e32 v0, 0x3000, v0
	s_mov_b32 m0, s0
	v_readfirstlane_b32 s0, v0
	s_mov_b32 m0, s0
	v_mov_b32_e32 v2, v220
	v_lshl_add_u64 v[0:1], v[70:71], 0, 64
	v_lshlrev_b32_e32 v2, 4, v2
	v_and_b32_e32 v2, 0xfffffc00, v2
	v_add_u32_e32 v3, 0x4000, v2
	s_nop 0
	v_readfirstlane_b32 s0, v3
	v_add_u32_e32 v3, 0x5000, v2
	s_mov_b32 m0, s0
	v_readfirstlane_b32 s0, v3
	v_add_u32_e32 v3, 0x6000, v2
	v_lshl_add_u64 v[0:1], v[72:73], 0, 64
	s_mov_b32 m0, s0
	v_readfirstlane_b32 s0, v3
	v_add_u32_e32 v2, 0x7000, v2
	v_lshl_add_u64 v[0:1], v[74:75], 0, 64
	s_mov_b32 m0, s0
	v_readfirstlane_b32 s0, v2
	v_lshl_add_u64 v[0:1], v[76:77], 0, 64
	s_mov_b32 m0, s0
	s_nop 0
	s_mov_b32 m0, s92
	s_nop 0
	global_load_lds_dwordx4 v133, s[88:89]
	s_add_u32 m0, m0, 0x1000
	s_nop 0
	global_load_lds_dwordx4 v134, s[88:89]
	s_add_u32 m0, m0, 0x1000
	s_nop 0
	global_load_lds_dwordx4 v135, s[88:89]
	s_add_u32 m0, m0, 0x1000
	s_nop 0
	global_load_lds_dwordx4 v136, s[88:89]
	s_add_u32 m0, m0, 0x1000
	s_nop 0
	global_load_lds_dwordx4 v133, s[90:91]
	s_add_u32 m0, m0, 0x1000
	s_nop 0
	global_load_lds_dwordx4 v134, s[90:91]
	s_add_u32 m0, m0, 0x1000
	s_nop 0
	global_load_lds_dwordx4 v135, s[90:91]
	s_add_u32 m0, m0, 0x1000
	s_nop 0
	global_load_lds_dwordx4 v136, s[90:91]

; __device__ __forceinline__ int tid_() { int t = threadIdx.x; asm volatile("" : "+v"(t)); return t; }
; __device__ __forceinline__ GemmOps gemm_ops(const u16* A, int lda, const u16* B, int ldb) {
;   const int lane = tid_() & 63, wid = tid_() >> 6, rr = lane >> 2, c = lane & 3;
;   const int R0 = wid * 16 + rr, R1 = (wid + 4) * 16 + rr;
;   GemmOps g;
;   g.a0 = A + (size_t)R0 * lda + ((c ^ ((R0 >> 2) & 3)) << 3);
;   g.a1 = A + (size_t)R1 * lda + ((c ^ ((R1 >> 2) & 3)) << 3);
;   g.b0 = B + (size_t)R0 * ldb + ((c ^ ((R0 >> 2) & 3)) << 3);
;   g.b1 = B + (size_t)R1 * ldb + ((c ^ ((R1 >> 2) & 3)) << 3);
;   return g;
; }
; __device__ __forceinline__ void gemm_issue(const GemmOps& g, int kt, int buf, char* L) {
;   const int wid = tid_() >> 6;
;   char* sb = L + buf * GEMM_STAGE_B;
;   __builtin_amdgcn_global_load_lds((const unsigned*)(g.a0 + kt * 32), (unsigned*)(sb + wid * 1024), 16, 0, 0);
;   __builtin_amdgcn_global_load_lds((const unsigned*)(g.a1 + kt * 32), (unsigned*)(sb + (wid + 4) * 1024), 16, 0, 0);
;   __builtin_amdgcn_global_load_lds((const unsigned*)(g.b0 + kt * 32), (unsigned*)(sb + 8192 + wid * 1024), 16, 0, 0);
;   __builtin_amdgcn_global_load_lds((const unsigned*)(g.b1 + kt * 32), (unsigned*)(sb + 8192 + (wid + 4) * 1024), 16, 0, 0);
; }
; __device__ __forceinline__ void gemm_prologue(const GemmOps& g, u16* lds) {
;   gemm_issue(g, 0, 0, (char*)lds); gemm_issue(g, 1, 1, (char*)lds);
; }
; __device__ void ph_gemm3(const P& p, u16* lds) {
;   const int wid = tid_() >> 6, wm = wid >> 1, wn = wid & 1;
;   const int NT = 16, NTILES = 264 * NT;
;   u16* Qb = p_proj;
;   int it = blockIdx.x;
;   if (it >= NTILES) return;
;   auto ops = [&](int t) __attribute__((always_inline)) { return gemm_ops(p_Abf + (size_t)(t / NT) * 128 * DM, DM, p_WqT + (size_t)(t % NT) * 128 * DM, DM); };
;   GemmOps g = ops(it);
;   __syncthreads();
;   gemm_prologue(g, lds);
.LBB0_691:
	s_cmp_lt_i32 s6, 8
	s_cselect_b64 s[0:1], -1, 0
	s_cmp_gt_i32 s7, 7
	s_cselect_b64 s[2:3], -1, 0
	s_and_b64 s[0:1], s[0:1], s[2:3]
	s_andn2_b64 vcc, exec, s[0:1]
	s_cbranch_vccnz .LBB0_753
	v_readlane_b32 s0, v228, 0
	v_mov_b32_e32 v0, v220
	s_cmpk_gt_i32 s0, 0x107f
	v_readlane_b32 s1, v228, 1
	s_cbranch_scc1 .LBB0_699
	v_readlane_b32 s0, v228, 2
	v_readlane_b32 s6, v228, 8
	v_readlane_b32 s1, v228, 3
	v_readlane_b32 s7, v228, 9
	s_add_u32 s0, s6, 0x8140000
	s_addc_u32 s1, s7, 0
	v_readlane_b32 s2, v228, 4
	s_add_u32 s12, s6, 0x3f40000
	v_readlane_b32 s10, v228, 0
	s_addc_u32 s13, s7, 0
	s_and_b32 s81, s10, 7
	s_lshr_b32 s82, s10, 3
	s_lshr_b32 s83, s82, 7
	s_and_b32 s84, s82, 127
	s_cmp_lt_u32 s83, 4
	s_cselect_b32 s85, 3, 0
	s_cselect_b32 s86, 7, 0
	s_lshr_b32 s87, s84, s85
	s_and_b32 s84, s84, s86
	s_lshl_b32 s83, s83, 3
	s_add_u32 s83, s83, s84
	s_mul_i32 s81, s81, 33
	s_add_u32 s81, s81, s83
	s_mul_i32 s81, s81, 16
	s_add_u32 s80, s81, s87
	s_ashr_i32 s2, s80, 31
	v_readlane_b32 s4, v228, 6
	s_lshr_b32 s2, s2, 28
	s_add_i32 s4, s80, s2
	v_readlane_b32 s3, v228, 5
	s_ashr_i32 s2, s4, 4
	s_ashr_i32 s3, s2, 31
	s_lshl_b64 s[2:3], s[2:3], 18
	s_add_u32 s2, s12, s2
	s_addc_u32 s3, s13, s3
	s_add_u32 s14, s6, 0x7c0000
	s_addc_u32 s15, s7, 0
	s_and_b32 s4, s4, -16
	v_mov_b32_e32 v1, v220
	v_mov_b32_e32 v2, v220
	v_readlane_b32 s5, v228, 7
	s_sub_i32 s4, s80, s4
	s_ashr_i32 s5, s4, 31
	v_lshrrev_b32_e32 v5, 4, v1
	v_lshrrev_b32_e32 v3, 2, v1
	v_ashrrev_i32_e32 v2, 2, v2
	v_xor_b32_e32 v1, v5, v1
	s_lshl_b64 s[4:5], s[4:5], 18
	v_bfi_b32 v2, -16, v2, v3
	v_lshlrev_b32_e32 v1, 4, v1
	s_add_u32 s4, s14, s4
	v_add_u32_e32 v4, 64, v2
	v_ashrrev_i32_e32 v3, 31, v2
	s_waitcnt vmcnt(0)
	v_and_b32_e32 v64, 48, v1
	v_mov_b32_e32 v1, v220
	s_addc_u32 s5, s15, s5
	s_mov_b64 s[88:89], s[2:3]
	s_mov_b64 s[90:91], s[4:5]
	v_lshlrev_b64 v[2:3], 11, v[2:3]
	v_ashrrev_i32_e32 v5, 31, v4
	s_waitcnt lgkmcnt(0)
	s_barrier
	v_lshl_add_u64 v[6:7], s[2:3], 0, v[2:3]
	v_mov_b32_e32 v65, 0
	v_lshlrev_b64 v[4:5], 11, v[4:5]
	v_lshl_add_u64 v[2:3], s[4:5], 0, v[2:3]
	v_lshlrev_b32_e32 v1, 4, v1
	v_lshl_add_u64 v[70:71], v[2:3], 0, v[64:65]
	v_lshl_add_u64 v[2:3], s[4:5], 0, v[4:5]
	v_and_b32_e32 v1, 0xfffffc00, v1
	v_lshl_add_u64 v[66:67], v[6:7], 0, v[64:65]
	v_lshl_add_u64 v[6:7], s[2:3], 0, v[4:5]
	v_lshl_add_u64 v[72:73], v[2:3], 0, v[64:65]
	v_readfirstlane_b32 s2, v1
	v_add_u32_e32 v2, 0x1000, v1
	s_mov_b32 m0, s2
	v_readfirstlane_b32 s2, v2
	v_add_u32_e32 v2, 0x2000, v1
	v_lshl_add_u64 v[68:69], v[6:7], 0, v[64:65]
	s_mov_b32 m0, s2
	v_readfirstlane_b32 s2, v2
	v_add_u32_e32 v1, 0x3000, v1
	s_mov_b32 m0, s2
	v_readfirstlane_b32 s2, v1
	s_mov_b32 m0, s2
	v_mov_b32_e32 v1, v220
	v_lshl_add_u64 v[2:3], v[66:67], 0, 64
	v_lshlrev_b32_e32 v1, 4, v1
	v_and_b32_e32 v1, 0xfffffc00, v1
	v_add_u32_e32 v4, 0x4000, v1
	v_and_b32_e32 v74, 64, v0
	v_readfirstlane_b32 s2, v4
	v_add_u32_e32 v4, 0x5000, v1
	s_mov_b32 m0, s2
	v_readfirstlane_b32 s2, v4
	v_add_u32_e32 v4, 0x6000, v1
	v_lshl_add_u64 v[2:3], v[68:69], 0, 64
	s_mov_b32 m0, s2
	v_readfirstlane_b32 s2, v4
	v_add_u32_e32 v1, 0x7000, v1
	v_lshl_add_u64 v[2:3], v[70:71], 0, 64
	s_mov_b32 m0, s2
	v_readfirstlane_b32 s2, v1
	v_lshl_add_u64 v[2:3], v[72:73], 0, 64
	s_mov_b32 m0, s2
	v_ashrrev_i32_e32 v0, 1, v0
	v_and_b32_e32 v75, 0xffffffc0, v0
	s_add_u32 s2, s6, 0x1b9f0600
	v_or_b32_e32 v76, 16, v75
	v_or_b32_e32 v77, 20, v75
	v_or_b32_e32 v78, 24, v75
	v_or_b32_e32 v79, 28, v75
	v_or_b32_e32 v80, 32, v75
	v_or_b32_e32 v81, 36, v75
	v_or_b32_e32 v82, 40, v75
	v_or_b32_e32 v83, 44, v75
	v_or_b32_e32 v84, 48, v75
	v_or_b32_e32 v85, 52, v75
	v_or_b32_e32 v86, 56, v75
	v_or_b32_e32 v87, 60, v75
	s_addc_u32 s3, s7, 0
	s_mov_b32 s16, 0x3ffffc0
	s_movk_i32 s17, 0x13c0
	s_mov_b64 s[4:5], 0x80
	s_mov_b64 s[6:7], 0xc0
	s_mov_b64 s[8:9], 0x100
	s_movk_i32 s18, 0x1100
	s_movk_i32 s19, 0x110
	s_movk_i32 s20, 0x440
	v_mov_b32_e32 v88, 0x358637bd
	s_mov_b32 s21, 0x800000
	s_mov_b32 s22, s10
	v_readlane_b32 s11, v228, 1
	v_lshrrev_b32_e32 v133, 3, v220
	v_lshlrev_b32_e32 v133, 11, v133
	v_bfe_u32 v134, v220, 4, 3
	v_and_b32_e32 v135, 7, v220
	v_xor_b32_e32 v134, v134, v135
	v_lshl_add_u32 v133, v134, 4, v133
	v_add_u32_e32 v134, 0x10000, v133
	v_add_u32_e32 v135, 0x20000, v133
	v_add_u32_e32 v136, 0x30000, v133
	v_and_b32_e32 v143, 15, v220
	v_bfe_u32 v144, v220, 4, 2
	v_bfe_u32 v145, v220, 1, 3
	v_xor_b32_e32 v144, v144, v145
	v_lshlrev_b32_e32 v144, 4, v144
	v_lshl_add_u32 v143, v143, 7, v144
	v_lshrrev_b32_e32 v144, 7, v220
	v_lshl_add_u32 v137, v144, 13, v143
	v_xor_b32_e32 v138, 64, v137
	v_bfe_u32 v144, v220, 6, 1
	v_lshl_add_u32 v139, v144, 13, v143
	v_add_u32_e32 v139, 0x4000, v139
	v_xor_b32_e32 v140, 64, v139
	v_lshl_add_u32 v141, v144, 10, v139
	v_lshl_add_u32 v142, v144, 10, v140
	v_readfirstlane_b32 s92, v220
	s_nop 0
	s_lshl_b32 s92, s92, 4
	s_add_u32 s93, s92, 0x8000
	s_mov_b32 m0, s92
	s_nop 0
	global_load_lds_dwordx4 v133, s[88:89]
	s_add_u32 m0, m0, 0x1000
	s_nop 0
	global_load_lds_dwordx4 v134, s[88:89]
	s_add_u32 m0, m0, 0x1000
	s_nop 0
	global_load_lds_dwordx4 v135, s[88:89]
	s_add_u32 m0, m0, 0x1000
	s_nop 0
	global_load_lds_dwordx4 v136, s[88:89]
	s_add_u32 m0, m0, 0x1000
	s_nop 0
	global_load_lds_dwordx4 v133, s[90:91]
	s_add_u32 m0, m0, 0x1000
	s_nop 0
	global_load_lds_dwordx4 v134, s[90:91]
	s_add_u32 m0, m0, 0x1000
	s_nop 0
	global_load_lds_dwordx4 v135, s[90:91]
	s_add_u32 m0, m0, 0x1000
	s_nop 0
	global_load_lds_dwordx4 v136, s[90:91]
	s_branch .LBB0_695

; __device__ __forceinline__ int tid_() { int t = threadIdx.x; asm volatile("" : "+v"(t)); return t; }
; __device__ __forceinline__ f32x4 mfma16(bf16x8 a, bf16x8 b, f32x4 c) { return __builtin_amdgcn_mfma_f32_16x16x32_bf16(a, b, c, 0, 0, 0); }
; #define RAW_BARRIER() do { asm volatile("s_waitcnt lgkmcnt(0)" ::: "memory"); __builtin_amdgcn_s_barrier(); } while (0)
; #define GEMM_STEP(J, BUF, NBUF) do { asm volatile("s_waitcnt vmcnt(4)" ::: "memory"); RAW_BARRIER(); \
;     if ((J) + 2 < nk) gemm_issue(g, (J) + 2, NBUF, L); comp(BUF); } while (0)
; __device__ __forceinline__ void gemm_main(f32x4 (&acc)[4][4], const GemmOps& g, int K, u16* lds) {
;   const int tid = tid_(), lane = tid & 63, wid = tid >> 6;
;   const int wm = wid >> 1, wn = wid & 1, fr = lane & 15, fq = lane >> 4;
;   char* L = (char*)lds;
;   int offA[4], offB[4];
; #pragma unroll
;   for (int i = 0; i < 4; ++i) {
;     const int Ra = wm * 64 + i * 16 + fr, Rb = wn * 64 + i * 16 + fr;
;     offA[i] = Ra * 64 + ((fq ^ ((Ra >> 2) & 3)) << 4);
;     offB[i] = 8192 + Rb * 64 + ((fq ^ ((Rb >> 2) & 3)) << 4);
;   }
;   auto comp = [&](int buf) __attribute__((always_inline)) {
;     const char* sb = L + buf * GEMM_STAGE_B;
;     bf16x8 a[4], b[4];
; #pragma unroll
;     for (int i = 0; i < 4; ++i) a[i] = *(const bf16x8*)(sb + offA[i]);
; #pragma unroll
;     for (int j = 0; j < 4; ++j) b[j] = *(const bf16x8*)(sb + offB[j]);
; #pragma unroll
;     for (int i = 0; i < 4; ++i)
; #pragma unroll
;       for (int j = 0; j < 4; ++j) acc[i][j] = mfma16(a[i], b[j], acc[i][j]);
;   };
;   const int nk = K >> 5;
;     ...
;   int j = 0;
;   for (; j + 3 <= nk - 1; j += 3) {
;     GEMM_STEP(j, 0, 2);
;     GEMM_STEP(j + 1, 1, 0);
;     GEMM_STEP(j + 2, 2, 1);
;   }
;   GEMM_STEP(j, 0, 2);
;   asm volatile("s_waitcnt vmcnt(0)" ::: "memory");
;   RAW_BARRIER();
;   comp(1);
;     ...
; }
; __device__ __forceinline__ void zero_acc(f32x4 (&acc)[4][4]) {
; #pragma unroll
;   for (int i = 0; i < 4; ++i)
; #pragma unroll
;     for (int j = 0; j < 4; ++j) acc[i][j] = f32x4{0.f, 0.f, 0.f, 0.f};
; }
.LBB0_696:
	v_mov_b32_e32 v60, 0
	v_mov_b32_e32 v61, 0
	v_mov_b32_e32 v62, 0
	v_mov_b32_e32 v63, 0
	v_mov_b32_e32 v56, 0
	v_mov_b32_e32 v57, 0
	v_mov_b32_e32 v58, 0
	v_mov_b32_e32 v59, 0
	v_mov_b32_e32 v52, 0
	v_mov_b32_e32 v53, 0
	v_mov_b32_e32 v54, 0
	v_mov_b32_e32 v55, 0
	v_mov_b32_e32 v48, 0
	v_mov_b32_e32 v49, 0
	v_mov_b32_e32 v50, 0
	v_mov_b32_e32 v51, 0
	v_mov_b32_e32 v44, 0
	v_mov_b32_e32 v45, 0
	v_mov_b32_e32 v46, 0
	v_mov_b32_e32 v47, 0
	v_mov_b32_e32 v40, 0
	v_mov_b32_e32 v41, 0
	v_mov_b32_e32 v42, 0
	v_mov_b32_e32 v43, 0
	v_mov_b32_e32 v36, 0
	v_mov_b32_e32 v37, 0
	v_mov_b32_e32 v38, 0
	v_mov_b32_e32 v39, 0
	v_mov_b32_e32 v32, 0
	v_mov_b32_e32 v33, 0
	v_mov_b32_e32 v34, 0
	v_mov_b32_e32 v35, 0
	v_mov_b32_e32 v28, 0
	v_mov_b32_e32 v29, 0
	v_mov_b32_e32 v30, 0
	v_mov_b32_e32 v31, 0
	v_mov_b32_e32 v24, 0
	v_mov_b32_e32 v25, 0
	v_mov_b32_e32 v26, 0
	v_mov_b32_e32 v27, 0
	v_mov_b32_e32 v20, 0
	v_mov_b32_e32 v21, 0
	v_mov_b32_e32 v22, 0
	v_mov_b32_e32 v23, 0
	v_mov_b32_e32 v16, 0
	v_mov_b32_e32 v17, 0
	v_mov_b32_e32 v18, 0
	v_mov_b32_e32 v19, 0
	v_mov_b32_e32 v0, 0
	v_mov_b32_e32 v1, 0
	v_mov_b32_e32 v2, 0
	v_mov_b32_e32 v3, 0
	v_mov_b32_e32 v4, 0
	v_mov_b32_e32 v5, 0
	v_mov_b32_e32 v6, 0
	v_mov_b32_e32 v7, 0
	v_mov_b32_e32 v8, 0
	v_mov_b32_e32 v9, 0
	v_mov_b32_e32 v10, 0
	v_mov_b32_e32 v11, 0
	v_mov_b32_e32 v12, 0
	v_mov_b32_e32 v13, 0
	v_mov_b32_e32 v14, 0
	v_mov_b32_e32 v15, 0
	s_mov_b32 s94, 7
.Lg3_k:
	s_waitcnt vmcnt(0)
	s_barrier
	s_add_u32 s88, s88, 0x80
	s_addc_u32 s89, s89, 0
	s_add_u32 s90, s90, 0x80
	s_addc_u32 s91, s91, 0
	s_mov_b32 m0, s93
	ds_read_b128 v[148:151], v137 offset:0
	global_load_lds_dwordx4 v133, s[88:89]
	s_add_u32 m0, m0, 0x1000
	ds_read_b128 v[152:155], v137 offset:2048
	global_load_lds_dwordx4 v134, s[88:89]
	s_add_u32 m0, m0, 0x1000
	ds_read_b128 v[156:159], v137 offset:4096
	global_load_lds_dwordx4 v135, s[88:89]
	s_add_u32 m0, m0, 0x1000
	ds_read_b128 v[160:163], v137 offset:6144
	global_load_lds_dwordx4 v136, s[88:89]
	s_add_u32 m0, m0, 0x1000
	ds_read_b128 v[180:183], v139 offset:0
	global_load_lds_dwordx4 v133, s[90:91]
	s_add_u32 m0, m0, 0x1000
	ds_read_b128 v[184:187], v139 offset:2048
	global_load_lds_dwordx4 v134, s[90:91]
	s_add_u32 m0, m0, 0x1400
	ds_read_b128 v[188:191], v139 offset:4096
	global_load_lds_dwordx4 v135, s[90:91]
	s_add_u32 m0, m0, 0x1000
	ds_read_b128 v[192:195], v139 offset:6144
	global_load_lds_dwordx4 v136, s[90:91]
	ds_read_b128 v[164:167], v138 offset:0
	ds_read_b128 v[168:171], v138 offset:2048
	ds_read_b128 v[172:175], v138 offset:4096
	ds_read_b128 v[176:179], v138 offset:6144
	ds_read_b128 v[196:199], v140 offset:0
	ds_read_b128 v[200:203], v140 offset:2048
	ds_read_b128 v[204:207], v140 offset:4096
	ds_read_b128 v[208:211], v140 offset:6144
	s_waitcnt lgkmcnt(8)
	v_mfma_f32_16x16x32_bf16 v[60:63], v[148:151], v[180:183], v[60:63]
	v_mfma_f32_16x16x32_bf16 v[56:59], v[148:151], v[184:187], v[56:59]
	v_mfma_f32_16x16x32_bf16 v[52:55], v[148:151], v[188:191], v[52:55]
	v_mfma_f32_16x16x32_bf16 v[48:51], v[148:151], v[192:195], v[48:51]
	v_mfma_f32_16x16x32_bf16 v[44:47], v[152:155], v[180:183], v[44:47]
	v_mfma_f32_16x16x32_bf16 v[40:43], v[152:155], v[184:187], v[40:43]
	v_mfma_f32_16x16x32_bf16 v[36:39], v[152:155], v[188:191], v[36:39]
	v_mfma_f32_16x16x32_bf16 v[32:35], v[152:155], v[192:195], v[32:35]
	v_mfma_f32_16x16x32_bf16 v[28:31], v[156:159], v[180:183], v[28:31]
	v_mfma_f32_16x16x32_bf16 v[24:27], v[156:159], v[184:187], v[24:27]
	v_mfma_f32_16x16x32_bf16 v[20:23], v[156:159], v[188:191], v[20:23]
	v_mfma_f32_16x16x32_bf16 v[16:19], v[156:159], v[192:195], v[16:19]
	v_mfma_f32_16x16x32_bf16 v[0:3], v[160:163], v[180:183], v[0:3]
	v_mfma_f32_16x16x32_bf16 v[4:7], v[160:163], v[184:187], v[4:7]
	v_mfma_f32_16x16x32_bf16 v[8:11], v[160:163], v[188:191], v[8:11]
	v_mfma_f32_16x16x32_bf16 v[12:15], v[160:163], v[192:195], v[12:15]
	s_waitcnt lgkmcnt(0)
	v_mfma_f32_16x16x32_bf16 v[60:63], v[164:167], v[196:199], v[60:63]
	v_mfma_f32_16x16x32_bf16 v[56:59], v[164:167], v[200:203], v[56:59]
	v_mfma_f32_16x16x32_bf16 v[52:55], v[164:167], v[204:207], v[52:55]
	v_mfma_f32_16x16x32_bf16 v[48:51], v[164:167], v[208:211], v[48:51]
	v_mfma_f32_16x16x32_bf16 v[44:47], v[168:171], v[196:199], v[44:47]
	v_mfma_f32_16x16x32_bf16 v[40:43], v[168:171], v[200:203], v[40:43]
	v_mfma_f32_16x16x32_bf16 v[36:39], v[168:171], v[204:207], v[36:39]
	v_mfma_f32_16x16x32_bf16 v[32:35], v[168:171], v[208:211], v[32:35]
	v_mfma_f32_16x16x32_bf16 v[28:31], v[172:175], v[196:199], v[28:31]
	v_mfma_f32_16x16x32_bf16 v[24:27], v[172:175], v[200:203], v[24:27]
	v_mfma_f32_16x16x32_bf16 v[20:23], v[172:175], v[204:207], v[20:23]
	v_mfma_f32_16x16x32_bf16 v[16:19], v[172:175], v[208:211], v[16:19]
	v_mfma_f32_16x16x32_bf16 v[0:3], v[176:179], v[196:199], v[0:3]
	v_mfma_f32_16x16x32_bf16 v[4:7], v[176:179], v[200:203], v[4:7]
	v_mfma_f32_16x16x32_bf16 v[8:11], v[176:179], v[204:207], v[8:11]
	v_mfma_f32_16x16x32_bf16 v[12:15], v[176:179], v[208:211], v[12:15]
	s_waitcnt vmcnt(0)
	s_barrier
; __device__ __forceinline__ int tid_() { int t = threadIdx.x; asm volatile("" : "+v"(t)); return t; }
; __device__ __forceinline__ f32x4 mfma16(bf16x8 a, bf16x8 b, f32x4 c) { return __builtin_amdgcn_mfma_f32_16x16x32_bf16(a, b, c, 0, 0, 0); }
; #define RAW_BARRIER() do { asm volatile("s_waitcnt lgkmcnt(0)" ::: "memory"); __builtin_amdgcn_s_barrier(); } while (0)
; #define GEMM_STEP(J, BUF, NBUF) do { asm volatile("s_waitcnt vmcnt(4)" ::: "memory"); RAW_BARRIER(); \
;     if ((J) + 2 < nk) gemm_issue(g, (J) + 2, NBUF, L); comp(BUF); } while (0)
; __device__ __forceinline__ void gemm_main(f32x4 (&acc)[4][4], const GemmOps& g, int K, u16* lds) {
;   const int tid = tid_(), lane = tid & 63, wid = tid >> 6;
;   const int wm = wid >> 1, wn = wid & 1, fr = lane & 15, fq = lane >> 4;
;   char* L = (char*)lds;
;   int offA[4], offB[4];
; #pragma unroll
;   for (int i = 0; i < 4; ++i) {
;     const int Ra = wm * 64 + i * 16 + fr, Rb = wn * 64 + i * 16 + fr;
;     offA[i] = Ra * 64 + ((fq ^ ((Ra >> 2) & 3)) << 4);
;     offB[i] = 8192 + Rb * 64 + ((fq ^ ((Rb >> 2) & 3)) << 4);
;   }
;   auto comp = [&](int buf) __attribute__((always_inline)) {
;     const char* sb = L + buf * GEMM_STAGE_B;
;     bf16x8 a[4], b[4];
; #pragma unroll
;     for (int i = 0; i < 4; ++i) a[i] = *(const bf16x8*)(sb + offA[i]);
; #pragma unroll
;     for (int j = 0; j < 4; ++j) b[j] = *(const bf16x8*)(sb + offB[j]);
; #pragma unroll
;     for (int i = 0; i < 4; ++i)
; #pragma unroll
;       for (int j = 0; j < 4; ++j) acc[i][j] = mfma16(a[i], b[j], acc[i][j]);
;   };
;   const int nk = K >> 5;
;     ...
;   int j = 0;
;   for (; j + 3 <= nk - 1; j += 3) {
;     GEMM_STEP(j, 0, 2);
;     GEMM_STEP(j + 1, 1, 0);
;     GEMM_STEP(j + 2, 2, 1);
;   }
;   GEMM_STEP(j, 0, 2);
;   asm volatile("s_waitcnt vmcnt(0)" ::: "memory");
;   RAW_BARRIER();
;   comp(1);
	s_add_u32 s88, s88, 0x80
	s_addc_u32 s89, s89, 0
	s_add_u32 s90, s90, 0x80
	s_addc_u32 s91, s91, 0
	s_mov_b32 m0, s92
	ds_read_b128 v[148:151], v137 offset:32768
	global_load_lds_dwordx4 v133, s[88:89]
	s_add_u32 m0, m0, 0x1000
	ds_read_b128 v[152:155], v137 offset:34816
	global_load_lds_dwordx4 v134, s[88:89]
	s_add_u32 m0, m0, 0x1000
	ds_read_b128 v[156:159], v137 offset:36864
	global_load_lds_dwordx4 v135, s[88:89]
	s_add_u32 m0, m0, 0x1000
	ds_read_b128 v[160:163], v137 offset:38912
	global_load_lds_dwordx4 v136, s[88:89]
	s_add_u32 m0, m0, 0x1000
	ds_read_b128 v[180:183], v141 offset:32768
	global_load_lds_dwordx4 v133, s[90:91]
	s_add_u32 m0, m0, 0x1000
	ds_read_b128 v[184:187], v141 offset:34816
	global_load_lds_dwordx4 v134, s[90:91]
	s_add_u32 m0, m0, 0x1000
	ds_read_b128 v[188:191], v141 offset:36864
	global_load_lds_dwordx4 v135, s[90:91]
	s_add_u32 m0, m0, 0x1000
	ds_read_b128 v[192:195], v141 offset:38912
	global_load_lds_dwordx4 v136, s[90:91]
	ds_read_b128 v[164:167], v138 offset:32768
	ds_read_b128 v[168:171], v138 offset:34816
	ds_read_b128 v[172:175], v138 offset:36864
	ds_read_b128 v[176:179], v138 offset:38912
	ds_read_b128 v[196:199], v142 offset:32768
	ds_read_b128 v[200:203], v142 offset:34816
	ds_read_b128 v[204:207], v142 offset:36864
	ds_read_b128 v[208:211], v142 offset:38912
	s_waitcnt lgkmcnt(8)
	v_mfma_f32_16x16x32_bf16 v[60:63], v[148:151], v[180:183], v[60:63]
	v_mfma_f32_16x16x32_bf16 v[56:59], v[148:151], v[184:187], v[56:59]
	v_mfma_f32_16x16x32_bf16 v[52:55], v[148:151], v[188:191], v[52:55]
	v_mfma_f32_16x16x32_bf16 v[48:51], v[148:151], v[192:195], v[48:51]
	v_mfma_f32_16x16x32_bf16 v[44:47], v[152:155], v[180:183], v[44:47]
	v_mfma_f32_16x16x32_bf16 v[40:43], v[152:155], v[184:187], v[40:43]
	v_mfma_f32_16x16x32_bf16 v[36:39], v[152:155], v[188:191], v[36:39]
	v_mfma_f32_16x16x32_bf16 v[32:35], v[152:155], v[192:195], v[32:35]
	v_mfma_f32_16x16x32_bf16 v[28:31], v[156:159], v[180:183], v[28:31]
	v_mfma_f32_16x16x32_bf16 v[24:27], v[156:159], v[184:187], v[24:27]
	v_mfma_f32_16x16x32_bf16 v[20:23], v[156:159], v[188:191], v[20:23]
	v_mfma_f32_16x16x32_bf16 v[16:19], v[156:159], v[192:195], v[16:19]
	v_mfma_f32_16x16x32_bf16 v[0:3], v[160:163], v[180:183], v[0:3]
	v_mfma_f32_16x16x32_bf16 v[4:7], v[160:163], v[184:187], v[4:7]
	v_mfma_f32_16x16x32_bf16 v[8:11], v[160:163], v[188:191], v[8:11]
	v_mfma_f32_16x16x32_bf16 v[12:15], v[160:163], v[192:195], v[12:15]
	s_waitcnt lgkmcnt(0)
	v_mfma_f32_16x16x32_bf16 v[60:63], v[164:167], v[196:199], v[60:63]
	v_mfma_f32_16x16x32_bf16 v[56:59], v[164:167], v[200:203], v[56:59]
	v_mfma_f32_16x16x32_bf16 v[52:55], v[164:167], v[204:207], v[52:55]
	v_mfma_f32_16x16x32_bf16 v[48:51], v[164:167], v[208:211], v[48:51]
	v_mfma_f32_16x16x32_bf16 v[44:47], v[168:171], v[196:199], v[44:47]
	v_mfma_f32_16x16x32_bf16 v[40:43], v[168:171], v[200:203], v[40:43]
	v_mfma_f32_16x16x32_bf16 v[36:39], v[168:171], v[204:207], v[36:39]
	v_mfma_f32_16x16x32_bf16 v[32:35], v[168:171], v[208:211], v[32:35]
	v_mfma_f32_16x16x32_bf16 v[28:31], v[172:175], v[196:199], v[28:31]
	v_mfma_f32_16x16x32_bf16 v[24:27], v[172:175], v[200:203], v[24:27]
	v_mfma_f32_16x16x32_bf16 v[20:23], v[172:175], v[204:207], v[20:23]
	v_mfma_f32_16x16x32_bf16 v[16:19], v[172:175], v[208:211], v[16:19]
	v_mfma_f32_16x16x32_bf16 v[0:3], v[176:179], v[196:199], v[0:3]
	v_mfma_f32_16x16x32_bf16 v[4:7], v[176:179], v[200:203], v[4:7]
	v_mfma_f32_16x16x32_bf16 v[8:11], v[176:179], v[204:207], v[8:11]
	v_mfma_f32_16x16x32_bf16 v[12:15], v[176:179], v[208:211], v[12:15]
	s_sub_u32 s94, s94, 1
	s_cmp_lg_u32 s94, 0
	s_cbranch_scc1 .Lg3_k
	s_waitcnt vmcnt(0)
	s_barrier
	s_add_u32 s88, s88, 0x80
	s_addc_u32 s89, s89, 0
	s_add_u32 s90, s90, 0x80
	s_addc_u32 s91, s91, 0
	s_mov_b32 m0, s93
	ds_read_b128 v[148:151], v137 offset:0
	global_load_lds_dwordx4 v133, s[88:89]
	s_add_u32 m0, m0, 0x1000
	ds_read_b128 v[152:155], v137 offset:2048
	global_load_lds_dwordx4 v134, s[88:89]
	s_add_u32 m0, m0, 0x1000
	ds_read_b128 v[156:159], v137 offset:4096
	global_load_lds_dwordx4 v135, s[88:89]
	s_add_u32 m0, m0, 0x1000
	ds_read_b128 v[160:163], v137 offset:6144
	global_load_lds_dwordx4 v136, s[88:89]
	s_add_u32 m0, m0, 0x1000
	ds_read_b128 v[180:183], v139 offset:0
	global_load_lds_dwordx4 v133, s[90:91]
	s_add_u32 m0, m0, 0x1000
	ds_read_b128 v[184:187], v139 offset:2048
	global_load_lds_dwordx4 v134, s[90:91]
	s_add_u32 m0, m0, 0x1400
	ds_read_b128 v[188:191], v139 offset:4096
	global_load_lds_dwordx4 v135, s[90:91]
	s_add_u32 m0, m0, 0x1000
	ds_read_b128 v[192:195], v139 offset:6144
	global_load_lds_dwordx4 v136, s[90:91]
	ds_read_b128 v[164:167], v138 offset:0
	ds_read_b128 v[168:171], v138 offset:2048
	ds_read_b128 v[172:175], v138 offset:4096
	ds_read_b128 v[176:179], v138 offset:6144
	ds_read_b128 v[196:199], v140 offset:0
	ds_read_b128 v[200:203], v140 offset:2048
	ds_read_b128 v[204:207], v140 offset:4096
	ds_read_b128 v[208:211], v140 offset:6144
	s_waitcnt lgkmcnt(8)
	v_mfma_f32_16x16x32_bf16 v[60:63], v[148:151], v[180:183], v[60:63]
	v_mfma_f32_16x16x32_bf16 v[56:59], v[148:151], v[184:187], v[56:59]
	v_mfma_f32_16x16x32_bf16 v[52:55], v[148:151], v[188:191], v[52:55]
	v_mfma_f32_16x16x32_bf16 v[48:51], v[148:151], v[192:195], v[48:51]
	v_mfma_f32_16x16x32_bf16 v[44:47], v[152:155], v[180:183], v[44:47]
	v_mfma_f32_16x16x32_bf16 v[40:43], v[152:155], v[184:187], v[40:43]
	v_mfma_f32_16x16x32_bf16 v[36:39], v[152:155], v[188:191], v[36:39]
	v_mfma_f32_16x16x32_bf16 v[32:35], v[152:155], v[192:195], v[32:35]
	v_mfma_f32_16x16x32_bf16 v[28:31], v[156:159], v[180:183], v[28:31]
	v_mfma_f32_16x16x32_bf16 v[24:27], v[156:159], v[184:187], v[24:27]
	v_mfma_f32_16x16x32_bf16 v[20:23], v[156:159], v[188:191], v[20:23]
	v_mfma_f32_16x16x32_bf16 v[16:19], v[156:159], v[192:195], v[16:19]
	v_mfma_f32_16x16x32_bf16 v[0:3], v[160:163], v[180:183], v[0:3]
	v_mfma_f32_16x16x32_bf16 v[4:7], v[160:163], v[184:187], v[4:7]
	v_mfma_f32_16x16x32_bf16 v[8:11], v[160:163], v[188:191], v[8:11]
	v_mfma_f32_16x16x32_bf16 v[12:15], v[160:163], v[192:195], v[12:15]
	s_waitcnt lgkmcnt(0)
; __device__ __forceinline__ f32x4 mfma16(bf16x8 a, bf16x8 b, f32x4 c) { return __builtin_amdgcn_mfma_f32_16x16x32_bf16(a, b, c, 0, 0, 0); }
; #define RAW_BARRIER() do { asm volatile("s_waitcnt lgkmcnt(0)" ::: "memory"); __builtin_amdgcn_s_barrier(); } while (0)
; #define GEMM_STEP(J, BUF, NBUF) do { asm volatile("s_waitcnt vmcnt(4)" ::: "memory"); RAW_BARRIER(); \
;     if ((J) + 2 < nk) gemm_issue(g, (J) + 2, NBUF, L); comp(BUF); } while (0)
; __device__ __forceinline__ void gemm_main(f32x4 (&acc)[4][4], const GemmOps& g, int K, u16* lds) {
;     ...
;   auto comp = [&](int buf) __attribute__((always_inline)) {
;     const char* sb = L + buf * GEMM_STAGE_B;
;     bf16x8 a[4], b[4];
; #pragma unroll
;     for (int i = 0; i < 4; ++i) a[i] = *(const bf16x8*)(sb + offA[i]);
; #pragma unroll
;     for (int j = 0; j < 4; ++j) b[j] = *(const bf16x8*)(sb + offB[j]);
; #pragma unroll
;     for (int i = 0; i < 4; ++i)
; #pragma unroll
;       for (int j = 0; j < 4; ++j) acc[i][j] = mfma16(a[i], b[j], acc[i][j]);
;   };
;   const int nk = K >> 5;
;     ...
;   int j = 0;
;   for (; j + 3 <= nk - 1; j += 3) {
;     GEMM_STEP(j, 0, 2);
;     GEMM_STEP(j + 1, 1, 0);
;     GEMM_STEP(j + 2, 2, 1);
;   }
;   GEMM_STEP(j, 0, 2);
;   asm volatile("s_waitcnt vmcnt(0)" ::: "memory");
;   RAW_BARRIER();
;   comp(1);
	v_mfma_f32_16x16x32_bf16 v[60:63], v[164:167], v[196:199], v[60:63]
	v_mfma_f32_16x16x32_bf16 v[56:59], v[164:167], v[200:203], v[56:59]
	v_mfma_f32_16x16x32_bf16 v[52:55], v[164:167], v[204:207], v[52:55]
	v_mfma_f32_16x16x32_bf16 v[48:51], v[164:167], v[208:211], v[48:51]
	v_mfma_f32_16x16x32_bf16 v[44:47], v[168:171], v[196:199], v[44:47]
	v_mfma_f32_16x16x32_bf16 v[40:43], v[168:171], v[200:203], v[40:43]
	v_mfma_f32_16x16x32_bf16 v[36:39], v[168:171], v[204:207], v[36:39]
	v_mfma_f32_16x16x32_bf16 v[32:35], v[168:171], v[208:211], v[32:35]
	v_mfma_f32_16x16x32_bf16 v[28:31], v[172:175], v[196:199], v[28:31]
	v_mfma_f32_16x16x32_bf16 v[24:27], v[172:175], v[200:203], v[24:27]
	v_mfma_f32_16x16x32_bf16 v[20:23], v[172:175], v[204:207], v[20:23]
	v_mfma_f32_16x16x32_bf16 v[16:19], v[172:175], v[208:211], v[16:19]
	v_mfma_f32_16x16x32_bf16 v[0:3], v[176:179], v[196:199], v[0:3]
	v_mfma_f32_16x16x32_bf16 v[4:7], v[176:179], v[200:203], v[4:7]
	v_mfma_f32_16x16x32_bf16 v[8:11], v[176:179], v[204:207], v[8:11]
	v_mfma_f32_16x16x32_bf16 v[12:15], v[176:179], v[208:211], v[12:15]
	s_waitcnt vmcnt(0)
	s_barrier
	ds_read_b128 v[148:151], v137 offset:32768
	ds_read_b128 v[152:155], v137 offset:34816
	ds_read_b128 v[156:159], v137 offset:36864
	ds_read_b128 v[160:163], v137 offset:38912
	ds_read_b128 v[180:183], v141 offset:32768
	ds_read_b128 v[184:187], v141 offset:34816
	ds_read_b128 v[188:191], v141 offset:36864
	ds_read_b128 v[192:195], v141 offset:38912
	ds_read_b128 v[164:167], v138 offset:32768
	ds_read_b128 v[168:171], v138 offset:34816
	ds_read_b128 v[172:175], v138 offset:36864
	ds_read_b128 v[176:179], v138 offset:38912
	ds_read_b128 v[196:199], v142 offset:32768
	ds_read_b128 v[200:203], v142 offset:34816
	ds_read_b128 v[204:207], v142 offset:36864
	ds_read_b128 v[208:211], v142 offset:38912
	s_waitcnt lgkmcnt(8)
	v_mfma_f32_16x16x32_bf16 v[60:63], v[148:151], v[180:183], v[60:63]
	v_mfma_f32_16x16x32_bf16 v[56:59], v[148:151], v[184:187], v[56:59]
	v_mfma_f32_16x16x32_bf16 v[52:55], v[148:151], v[188:191], v[52:55]
	v_mfma_f32_16x16x32_bf16 v[48:51], v[148:151], v[192:195], v[48:51]
	v_mfma_f32_16x16x32_bf16 v[44:47], v[152:155], v[180:183], v[44:47]
	v_mfma_f32_16x16x32_bf16 v[40:43], v[152:155], v[184:187], v[40:43]
	v_mfma_f32_16x16x32_bf16 v[36:39], v[152:155], v[188:191], v[36:39]
	v_mfma_f32_16x16x32_bf16 v[32:35], v[152:155], v[192:195], v[32:35]
	v_mfma_f32_16x16x32_bf16 v[28:31], v[156:159], v[180:183], v[28:31]
	v_mfma_f32_16x16x32_bf16 v[24:27], v[156:159], v[184:187], v[24:27]
	v_mfma_f32_16x16x32_bf16 v[20:23], v[156:159], v[188:191], v[20:23]
	v_mfma_f32_16x16x32_bf16 v[16:19], v[156:159], v[192:195], v[16:19]
	v_mfma_f32_16x16x32_bf16 v[0:3], v[160:163], v[180:183], v[0:3]
	v_mfma_f32_16x16x32_bf16 v[4:7], v[160:163], v[184:187], v[4:7]
	v_mfma_f32_16x16x32_bf16 v[8:11], v[160:163], v[188:191], v[8:11]
	v_mfma_f32_16x16x32_bf16 v[12:15], v[160:163], v[192:195], v[12:15]
	s_waitcnt lgkmcnt(0)
	v_mfma_f32_16x16x32_bf16 v[60:63], v[164:167], v[196:199], v[60:63]
	v_mfma_f32_16x16x32_bf16 v[56:59], v[164:167], v[200:203], v[56:59]
	v_mfma_f32_16x16x32_bf16 v[52:55], v[164:167], v[204:207], v[52:55]
	v_mfma_f32_16x16x32_bf16 v[48:51], v[164:167], v[208:211], v[48:51]
	v_mfma_f32_16x16x32_bf16 v[44:47], v[168:171], v[196:199], v[44:47]
	v_mfma_f32_16x16x32_bf16 v[40:43], v[168:171], v[200:203], v[40:43]
	v_mfma_f32_16x16x32_bf16 v[36:39], v[168:171], v[204:207], v[36:39]
	v_mfma_f32_16x16x32_bf16 v[32:35], v[168:171], v[208:211], v[32:35]
	v_mfma_f32_16x16x32_bf16 v[28:31], v[172:175], v[196:199], v[28:31]
	v_mfma_f32_16x16x32_bf16 v[24:27], v[172:175], v[200:203], v[24:27]
	v_mfma_f32_16x16x32_bf16 v[20:23], v[172:175], v[204:207], v[20:23]
	v_mfma_f32_16x16x32_bf16 v[16:19], v[172:175], v[208:211], v[16:19]
	v_mfma_f32_16x16x32_bf16 v[0:3], v[176:179], v[196:199], v[0:3]
	v_mfma_f32_16x16x32_bf16 v[4:7], v[176:179], v[200:203], v[4:7]
	v_mfma_f32_16x16x32_bf16 v[8:11], v[176:179], v[204:207], v[8:11]
	v_mfma_f32_16x16x32_bf16 v[12:15], v[176:179], v[208:211], v[12:15]
	s_waitcnt lgkmcnt(0)
	s_barrier
; __device__ __forceinline__ int tid_() { int t = threadIdx.x; asm volatile("" : "+v"(t)); return t; }
; __device__ __forceinline__ GemmOps gemm_ops(const u16* A, int lda, const u16* B, int ldb) {
;   const int lane = tid_() & 63, wid = tid_() >> 6, rr = lane >> 2, c = lane & 3;
;   const int R0 = wid * 16 + rr, R1 = (wid + 4) * 16 + rr;
;   GemmOps g;
;   g.a0 = A + (size_t)R0 * lda + ((c ^ ((R0 >> 2) & 3)) << 3);
;   g.a1 = A + (size_t)R1 * lda + ((c ^ ((R1 >> 2) & 3)) << 3);
;   g.b0 = B + (size_t)R0 * ldb + ((c ^ ((R0 >> 2) & 3)) << 3);
;   g.b1 = B + (size_t)R1 * ldb + ((c ^ ((R1 >> 2) & 3)) << 3);
;   return g;
; }
; __device__ __forceinline__ void gemm_issue(const GemmOps& g, int kt, int buf, char* L) {
;   const int wid = tid_() >> 6;
;   char* sb = L + buf * GEMM_STAGE_B;
;   __builtin_amdgcn_global_load_lds((const unsigned*)(g.a0 + kt * 32), (unsigned*)(sb + wid * 1024), 16, 0, 0);
;   __builtin_amdgcn_global_load_lds((const unsigned*)(g.a1 + kt * 32), (unsigned*)(sb + (wid + 4) * 1024), 16, 0, 0);
;   __builtin_amdgcn_global_load_lds((const unsigned*)(g.b0 + kt * 32), (unsigned*)(sb + 8192 + wid * 1024), 16, 0, 0);
;   __builtin_amdgcn_global_load_lds((const unsigned*)(g.b1 + kt * 32), (unsigned*)(sb + 8192 + (wid + 4) * 1024), 16, 0, 0);
; }
; __device__ __forceinline__ void gemm_prologue(const GemmOps& g, u16* lds) {
;   gemm_issue(g, 0, 0, (char*)lds); gemm_issue(g, 1, 1, (char*)lds);
; }
; __device__ void ph_gemm3(const P& p, u16* lds) {
;     ...
;     const int itn = it + gridDim.x; const bool more = itn < NTILES;
;     __syncthreads();
;     if (more) { g = ops(itn); gemm_prologue(g, lds); }
	s_nop 7
	v_readlane_b32 s10, v228, 10
	s_add_i32 s22, s23, s10
	v_readlane_b32 s11, v228, 11
	s_cmpk_gt_i32 s22, 0x107f
	s_cselect_b64 s[10:11], -1, 0
	s_and_b64 vcc, exec, s[10:11]
	s_cbranch_vccnz .LBB0_694
	s_and_b32 s81, s22, 7
	s_lshr_b32 s82, s22, 3
	s_lshr_b32 s83, s82, 7
	s_and_b32 s84, s82, 127
	s_cmp_lt_u32 s83, 4
	s_cselect_b32 s85, 3, 0
	s_cselect_b32 s86, 7, 0
	s_lshr_b32 s87, s84, s85
	s_and_b32 s84, s84, s86
	s_lshl_b32 s83, s83, 3
	s_add_u32 s83, s83, s84
	s_mul_i32 s81, s81, 33
	s_add_u32 s81, s81, s83
	s_mul_i32 s81, s81, 16
	s_add_u32 s80, s81, s87
	s_ashr_i32 s24, s80, 31
	s_lshr_b32 s24, s24, 28
	s_add_i32 s26, s80, s24
	s_ashr_i32 s24, s26, 4
	s_ashr_i32 s25, s24, 31
	s_lshl_b64 s[24:25], s[24:25], 18
	s_add_u32 s24, s12, s24
	v_mov_b32_e32 v64, v220
	v_mov_b32_e32 v66, v220
	s_addc_u32 s25, s13, s25
	s_and_b32 s26, s26, -16
	s_sub_i32 s26, s80, s26
	v_lshrrev_b32_e32 v67, 2, v64
	v_ashrrev_i32_e32 v66, 2, v66
	s_ashr_i32 s27, s26, 31
	v_bfi_b32 v66, -16, v66, v67
	s_lshl_b64 s[26:27], s[26:27], 18
	v_add_u32_e32 v68, 64, v66
	v_lshrrev_b32_e32 v69, 4, v64
	s_add_u32 s26, s14, s26
	v_ashrrev_i32_e32 v67, 31, v66
	v_xor_b32_e32 v64, v69, v64
	v_ashrrev_i32_e32 v69, 31, v68
	s_addc_u32 s27, s15, s27
	s_mov_b64 s[88:89], s[24:25]
	s_mov_b64 s[90:91], s[26:27]
	v_lshlrev_b64 v[70:71], 11, v[66:67]
	v_lshlrev_b32_e32 v64, 4, v64
	v_lshlrev_b64 v[72:73], 11, v[68:69]
	v_lshl_add_u64 v[66:67], s[24:25], 0, v[70:71]
	v_and_b32_e32 v64, 48, v64
	v_lshl_add_u64 v[68:69], s[24:25], 0, v[72:73]
	v_lshl_add_u64 v[70:71], s[26:27], 0, v[70:71]
	v_lshl_add_u64 v[72:73], s[26:27], 0, v[72:73]
	v_lshl_add_u64 v[66:67], v[66:67], 0, v[64:65]
	v_lshl_add_u64 v[68:69], v[68:69], 0, v[64:65]
	v_lshl_add_u64 v[70:71], v[70:71], 0, v[64:65]
	v_lshl_add_u64 v[72:73], v[72:73], 0, v[64:65]
	v_mov_b32_e32 v64, v220
	v_lshl_add_u64 v[90:91], v[66:67], 0, 64
	v_lshlrev_b32_e32 v64, 4, v64
	v_and_b32_e32 v64, 0xfffffc00, v64
	v_add_u32_e32 v89, 0x1000, v64
	v_readfirstlane_b32 s24, v64
	s_mov_b32 m0, s24
	v_readfirstlane_b32 s24, v89
	v_add_u32_e32 v89, 0x2000, v64
	s_mov_b32 m0, s24
	v_readfirstlane_b32 s24, v89
	v_add_u32_e32 v64, 0x3000, v64
	s_mov_b32 m0, s24
	v_readfirstlane_b32 s24, v64
	s_mov_b32 m0, s24
	v_mov_b32_e32 v64, v220
	s_nop 0
	v_lshlrev_b32_e32 v64, 4, v64
	v_and_b32_e32 v64, 0xfffffc00, v64
	v_add_u32_e32 v89, 0x4000, v64
	s_nop 0
	v_readfirstlane_b32 s24, v89
	v_add_u32_e32 v89, 0x5000, v64
	s_mov_b32 m0, s24
	v_readfirstlane_b32 s24, v89
	v_add_u32_e32 v89, 0x6000, v64
	v_lshl_add_u64 v[90:91], v[68:69], 0, 64
	s_mov_b32 m0, s24
	v_readfirstlane_b32 s24, v89
	v_add_u32_e32 v64, 0x7000, v64
	v_lshl_add_u64 v[90:91], v[70:71], 0, 64
	s_mov_b32 m0, s24
	v_readfirstlane_b32 s24, v64
	v_lshl_add_u64 v[90:91], v[72:73], 0, 64
	s_mov_b32 m0, s24
	s_nop 0
	s_mov_b32 m0, s92
	s_nop 0
	global_load_lds_dwordx4 v133, s[88:89]
	s_add_u32 m0, m0, 0x1000
	s_nop 0
	global_load_lds_dwordx4 v134, s[88:89]
	s_add_u32 m0, m0, 0x1000
	s_nop 0
	global_load_lds_dwordx4 v135, s[88:89]
	s_add_u32 m0, m0, 0x1000
	s_nop 0
	global_load_lds_dwordx4 v136, s[88:89]
	s_add_u32 m0, m0, 0x1000
	s_nop 0
	global_load_lds_dwordx4 v133, s[90:91]
	s_add_u32 m0, m0, 0x1000
	s_nop 0
	global_load_lds_dwordx4 v134, s[90:91]
	s_add_u32 m0, m0, 0x1000
	s_nop 0
	global_load_lds_dwordx4 v135, s[90:91]
	s_add_u32 m0, m0, 0x1000
	s_nop 0
	global_load_lds_dwordx4 v136, s[90:91]
	s_branch .LBB0_694

; __global__ void __launch_bounds__(256, 2) mega(P p) {
;   __shared__ __attribute__((aligned(16))) float lds_f[14340];
	.amdhsa_kernel _Z4mega1P
		.amdhsa_group_segment_fixed_size 66560
		.amdhsa_private_segment_fixed_size 0
		.amdhsa_kernarg_size 488
		.amdhsa_user_sgpr_count 2
		.amdhsa_user_sgpr_dispatch_ptr 0
		.amdhsa_user_sgpr_queue_ptr 0
		.amdhsa_user_sgpr_kernarg_segment_ptr 1
		.amdhsa_user_sgpr_dispatch_id 0
		.amdhsa_user_sgpr_kernarg_preload_length 0
		.amdhsa_user_sgpr_kernarg_preload_offset 0
		.amdhsa_user_sgpr_private_segment_size 0
		.amdhsa_uses_dynamic_stack 0
		.amdhsa_enable_private_segment 0
		.amdhsa_system_sgpr_workgroup_id_x 1
		.amdhsa_system_sgpr_workgroup_id_y 0
		.amdhsa_system_sgpr_workgroup_id_z 0
		.amdhsa_system_sgpr_workgroup_info 0
		.amdhsa_system_vgpr_workitem_id 2
		.amdhsa_next_free_vgpr 229
		.amdhsa_next_free_sgpr 98
		.amdhsa_accum_offset 232
		.amdhsa_reserve_vcc 1
		.amdhsa_float_round_mode_32 0
		.amdhsa_float_round_mode_16_64 0
		.amdhsa_float_denorm_mode_32 3
		.amdhsa_float_denorm_mode_16_64 3
		.amdhsa_dx10_clamp 1
		.amdhsa_ieee_mode 1
		.amdhsa_fp16_overflow 0
		.amdhsa_tg_split 0
		.amdhsa_exception_fp_ieee_invalid_op 0
		.amdhsa_exception_fp_denorm_src 0
		.amdhsa_exception_fp_ieee_div_zero 0
		.amdhsa_exception_fp_ieee_overflow 0
		.amdhsa_exception_fp_ieee_underflow 0
		.amdhsa_exception_fp_ieee_inexact 0
		.amdhsa_exception_int_div_zero 0
	.end_amdhsa_kernel

; __global__ void __launch_bounds__(256, 2) mega(P p) {
;   __shared__ __attribute__((aligned(16))) float lds_f[14340];
amdhsa.kernels:
  - .agpr_count:     0
    .args:
      - .offset:         0
        .size:           232
        .value_kind:     by_value
      - .offset:         232
        .size:           4
        .value_kind:     hidden_block_count_x
      - .offset:         236
        .size:           4
        .value_kind:     hidden_block_count_y
      - .offset:         240
        .size:           4
        .value_kind:     hidden_block_count_z
      - .offset:         244
        .size:           2
        .value_kind:     hidden_group_size_x
      - .offset:         246
        .size:           2
        .value_kind:     hidden_group_size_y
      - .offset:         248
        .size:           2
        .value_kind:     hidden_group_size_z
      - .offset:         250
        .size:           2
        .value_kind:     hidden_remainder_x
      - .offset:         252
        .size:           2
        .value_kind:     hidden_remainder_y
      - .offset:         254
        .size:           2
        .value_kind:     hidden_remainder_z
      - .offset:         272
        .size:           8
        .value_kind:     hidden_global_offset_x
      - .offset:         280
        .size:           8
        .value_kind:     hidden_global_offset_y
      - .offset:         288
        .size:           8
        .value_kind:     hidden_global_offset_z
      - .offset:         296
        .size:           2
        .value_kind:     hidden_grid_dims
      - .offset:         320
        .size:           8
        .value_kind:     hidden_multigrid_sync_arg
    .group_segment_fixed_size: 66560
    .kernarg_segment_align: 8
    .kernarg_segment_size: 488
    .language:       OpenCL C
    .language_version:
      - 2
      - 0
    .max_flat_workgroup_size: 256
    .name:           _Z4mega1P
    .private_segment_fixed_size: 0
    .sgpr_count:     104
    .sgpr_spill_count: 87
    .symbol:         _Z4mega1P.kd
    .uniform_work_group_size: 1
    .uses_dynamic_stack: false
    .vgpr_count:     229
    .vgpr_spill_count: 0
    .wavefront_size: 64
